# v18: + out-proj sample tile staged through LDS; NT=4 sample tiles issue the second K half as coalesced register loads up front; epilogue row-scale loads hoisted to the unit start so the epilogue has n
# baseline (speedup 1.0000x reference)
;     __device__ __forceinline__ void operator()(const f32x4 (&acc)[2][2][4][2], const Unit& u, int wr, int wc, int fr, int fq) const {
;         const int row0 = u.pm * BM + wr * 64 + fr; const int col0 = u.pn * BM + wc * 32 + 8 * fq;
; #pragma unroll
;         for (int ai = 0; ai < 2; ++ai)
; #pragma unroll
;             for (int m = 0; m < 4; ++m) { const int row_ = row0 + ai * HALF + m * 16; bf16_t* rowp = O + (size_t)(row_ >> 11) * gs + (size_t)(row_ & 2047) * ldc + col0; const float sc = rs ? rs[row0 + ai * HALF + m * 16] : 1.f;
.LBB0_28:
	s_lshl_b32 vcc_lo, s25, 8
	s_add_i32 vcc_lo, vcc_lo, s75
	v_or_b32_e32 v152, vcc_lo, v153
	v_lshlrev_b32_e32 v152, 2, v152
	s_and_b64 vcc, exec, s[66:67]
	s_cbranch_vccz .Lrsh_up_nors
	global_load_dword v154, v152, s[82:83]
	global_load_dword v187, v152, s[82:83] offset:64
	global_load_dword v248, v152, s[82:83] offset:128
	global_load_dword v249, v152, s[82:83] offset:192
	global_load_dword v250, v152, s[82:83] offset:512
	global_load_dword v251, v152, s[82:83] offset:576
	global_load_dword v169, v152, s[82:83] offset:640
	global_load_dword v152, v152, s[82:83] offset:704
	s_branch .Lrsh_up_go
.Lrsh_up_nors:
	v_mov_b32_e32 v154, 1.0
	v_mov_b32_e32 v187, 1.0
	v_mov_b32_e32 v248, 1.0
	v_mov_b32_e32 v249, 1.0
	v_mov_b32_e32 v250, 1.0
	v_mov_b32_e32 v251, 1.0
	v_mov_b32_e32 v169, 1.0
	v_mov_b32_e32 v152, 1.0

;     __device__ __forceinline__ void operator()(const f32x4 (&acc)[2][2][4][2], const Unit& u, int wr, int wc, int fr, int fq) const {
;     ...
;             for (int m = 0; m < 4; ++m) { const int row_ = row0 + ai * HALF + m * 16; bf16_t* rowp = O + (size_t)(row_ >> 11) * gs + (size_t)(row_ & 2047) * ldc + col0; const float sc = rs ? rs[row0 + ai * HALF + m * 16] : 1.f;
.LBB0_38:
	s_lshl_b32 s13, s25, 8
	s_add_i32 s13, s13, s75
	v_or_b32_e32 v150, s13, v153
	s_waitcnt vmcnt(16)
	v_mov_b32_e32 v200, v154
	v_mov_b32_e32 v202, v187
	v_mov_b32_e32 v204, v248
	v_mov_b32_e32 v206, v249
	v_mov_b32_e32 v208, v250
	v_mov_b32_e32 v210, v251
	v_mov_b32_e32 v212, v169
	v_mov_b32_e32 v214, v152
	v_mov_b32_e32 v169, 0x1000

; __device__ __forceinline__ unsigned cvt_pk_bf16(float lo, float hi) { unsigned r; asm volatile("v_cvt_pk_bf16_f32 %0, %1, %2" : "=v"(r) : "v"(lo), "v"(hi)); return r; }
; __device__ __forceinline__ float relu_sq(float x) { float r; asm volatile("v_max_f32 %0, 0, %1" : "=v"(r) : "v"(x)); return r * r; }
;     __device__ __forceinline__ void operator()(const f32x4 (&acc)[2][2][4][2], const Unit& u, int wr, int wc, int fr, int fq) const {
;     ...
;             for (int m = 0; m < 4; ++m) { const int row_ = row0 + ai * HALF + m * 16; bf16_t* rowp = O + (size_t)(row_ >> 11) * gs + (size_t)(row_ & 2047) * ldc + col0; const float sc = rs ? rs[row0 + ai * HALF + m * 16] : 1.f;
; #pragma unroll
;                 for (int bj = 0; bj < 2; ++bj) { f32x4 v0 = acc[ai][bj][m][0] * sc, v1 = acc[ai][bj][m][1] * sc;
;                     if (ACT == 1) {
; #pragma unroll
;                         for (int e = 0; e < 4; ++e) { v0[e] = relu_sq(v0[e]); v1[e] = relu_sq(v1[e]); } }
;                     u32x4 w; w.x = cvt_pk_bf16(v0[0], v0[1]); w.y = cvt_pk_bf16(v0[2], v0[3]); w.z = cvt_pk_bf16(v1[0], v1[1]); w.w = cvt_pk_bf16(v1[2], v1[3]);
;                     *(u32x4*)(rowp + bj * HALF) = w; } }
.LBB0_40:
	s_ashr_i32 s13, s13, 11
	s_mul_hi_i32 s19, s13, 0x1040000
	s_mul_i32 s13, s13, 0x1040000
	v_and_b32_e32 v128, 0x7cf, v150
	s_add_u32 s18, s64, s13
	v_mul_u32_u24_e32 v128, 0x1040, v128
	s_nop 0
	v_pk_mul_f32 v[124:125], v[124:125], v[200:201] op_sel_hi:[1,0]
	v_pk_mul_f32 v[120:121], v[120:121], v[200:201] op_sel_hi:[1,0]
	s_addc_u32 s19, s65, s19
	v_lshlrev_b32_e32 v128, 1, v128
	v_max_f32 v124, 0, v124
	v_max_f32 v120, 0, v120
	v_lshl_add_u64 v[158:159], s[18:19], 0, v[128:129]
	v_pk_mul_f32 v[122:123], v[122:123], v[200:201] op_sel_hi:[1,0]
	v_mul_f32_e32 v128, v120, v120
	v_max_f32 v120, 0, v125
	v_max_f32 v121, 0, v121
	v_lshl_or_b32 v148, s24, 8, v152
	v_pk_mul_f32 v[126:127], v[126:127], v[200:201] op_sel_hi:[1,0]
	v_mul_f32_e32 v125, v121, v121
	v_max_f32 v121, 0, v126
	v_max_f32 v122, 0, v122
	v_ashrrev_i32_e32 v149, 31, v148
	v_mul_f32_e32 v126, v122, v122
	v_max_f32 v122, 0, v127
	v_max_f32 v123, 0, v123
	v_lshl_add_u64 v[158:159], v[148:149], 1, v[158:159]
	v_mul_f32_e32 v120, v120, v120
	v_mul_f32_e32 v121, v121, v121
	v_mul_f32_e32 v122, v122, v122
	v_mul_f32_e32 v123, v123, v123
	v_pk_mul_f32 v[116:117], v[116:117], v[200:201] op_sel_hi:[1,0]
	v_pk_mul_f32 v[112:113], v[112:113], v[200:201] op_sel_hi:[1,0]
	v_mul_f32_e32 v124, v124, v124
	v_cvt_pk_bf16_f32 v120, v124, v120
	v_cvt_pk_bf16_f32 v121, v121, v122
	v_cvt_pk_bf16_f32 v122, v128, v125
	v_cvt_pk_bf16_f32 v123, v126, v123
	ds_write_b128 v154, v[120:123]
	ds_read_b128 v[248:251], v187
	s_nop 1
	v_max_f32 v116, 0, v116
	v_max_f32 v112, 0, v112
	v_pk_mul_f32 v[114:115], v[114:115], v[200:201] op_sel_hi:[1,0]
	v_pk_mul_f32 v[118:119], v[118:119], v[200:201] op_sel_hi:[1,0]
	v_mul_f32_e32 v120, v112, v112
	v_max_f32 v112, 0, v117
	v_max_f32 v113, 0, v113
	v_mul_f32_e32 v116, v116, v116
	v_mul_f32_e32 v117, v113, v113
	v_max_f32 v113, 0, v118
	v_max_f32 v114, 0, v114
	v_mul_f32_e32 v112, v112, v112
	v_mul_f32_e32 v118, v114, v114
	v_max_f32 v114, 0, v119
	v_max_f32 v115, 0, v115
	v_mul_f32_e32 v113, v113, v113
	v_mul_f32_e32 v114, v114, v114
	v_mul_f32_e32 v115, v115, v115
	v_cvt_pk_bf16_f32 v112, v116, v112
	v_cvt_pk_bf16_f32 v113, v113, v114
	v_cvt_pk_bf16_f32 v114, v120, v117
	v_cvt_pk_bf16_f32 v115, v118, v115
	s_waitcnt lgkmcnt(0)
	global_store_dwordx4 v[158:159], v[248:251], off
	ds_write_b128 v154, v[112:115]
	ds_read_b128 v[248:251], v187
	s_nop 1
	s_nop 0
	s_nop 0
	v_or_b32_e32 v112, 16, v150
	s_nop 0

; template <int NT, int ACT, int K>
; __device__ __forceinline__ void small_gemm_tile(LAS unsigned char* lds, const bf16* __restrict__ A, const bf16* __restrict__ Bt, bf16* __restrict__ O, int ldc, int lda, int ldb, const float* __restrict__ rs, int m0, int n0, int tid) {
;     constexpr int NC = 16 * NT, KW = K / 8, NCH = KW / 128;
;     const int wave = __builtin_amdgcn_readfirstlane(tid >> 6), lane = tid & 63, fr = lane & 15, fq = lane >> 4;
;     const bf16* ap = A + (size_t)(m0 + fr) * lda + wave * KW + fq * 8;
;     const bf16* bp = Bt + (size_t)(n0 + fr) * ldb + wave * KW + fq * 8;
;     f32x4 acc[4][NT];
; #pragma unroll
;     for (int m = 0; m < 4; ++m)
; #pragma unroll
;         for (int n = 0; n < NT; ++n) acc[m][n] = (f32x4){0.f, 0.f, 0.f, 0.f};
;     if constexpr (NCH == 1) {
;         bf16x8 fa[4][4], fb[4][NT];
; #pragma unroll
;         for (int s_ = 0; s_ < 4; ++s_) {
; #pragma unroll
;             for (int m = 0; m < 4; ++m) fa[s_][m] = *(const bf16x8*)(ap + (size_t)m * 16 * lda + s_ * 32);
; #pragma unroll
;             for (int n = 0; n < NT; ++n) fb[s_][n] = *(const bf16x8*)(bp + (size_t)n * 16 * ldb + s_ * 32); }
;         __builtin_amdgcn_sched_barrier(0);
; #pragma unroll
;         for (int s_ = 0; s_ < 4; ++s_)
; #pragma unroll
;             for (int m = 0; m < 4; ++m)
; #pragma unroll
;                 for (int n = 0; n < NT; ++n) acc[m][n] = __builtin_amdgcn_mfma_f32_16x16x32_bf16(fa[s_][m], fb[s_][n], acc[m][n], 0, 0, 0);
;         __builtin_amdgcn_sched_barrier(0);
.Lws_nc_up:
	s_waitcnt vmcnt(3)
	v_ashrrev_i32_e32 v1, 31, v186
	v_lshrrev_b32_e32 v1, 29, v1
	v_add_u32_e32 v1, v186, v1
	s_waitcnt vmcnt(0)
	v_bfe_u32 v0, v186, 4, 2
	v_ashrrev_i32_e32 v13, 3, v1
	v_bfe_i32 v1, v186, 28, 1
	v_lshlrev_b32_e32 v2, 3, v0
	v_lshlrev_b32_e32 v14, 10, v0
	v_lshlrev_b32_e32 v0, 3, v186
	v_lshrrev_b32_e32 v1, 26, v1
	v_add_u32_e32 v1, v0, v1
	v_and_b32_e32 v1, 0xffffffc0, v1
	v_lshlrev_b32_e32 v3, 2, v153
	v_lshl_add_u32 v4, v186, 5, 0
	v_sub_u32_e32 v0, v0, v1
	v_add_u32_e32 v5, 0x10000, v4
	v_add_u32_e32 v6, 0x10010, v4
	v_add_u32_e32 v7, 0x14000, v4
	v_add_u32_e32 v8, 0x14010, v4
	v_add_u32_e32 v9, 0x18000, v4
	v_add_u32_e32 v10, 0x18010, v4
	v_add_u32_e32 v11, 0x1c000, v4
	v_add_u32_e32 v12, 0x1c010, v4
	v_ashrrev_i32_e32 v1, 31, v0
	v_add3_u32 v14, 0, v3, v14
	s_waitcnt lgkmcnt(0)
	s_lshl_b32 s2, s3, 6
	v_lshlrev_b32_e32 v2, 1, v2
	v_readlane_b32 s6, v253, 51
	s_mov_b32 s7, s60
	v_and_b32_e32 v230, 63, v186
	v_lshrrev_b32_e32 v231, 3, v230
	v_and_b32_e32 v232, 7, v230
	v_lshrrev_b32_e32 v233, 1, v231
	v_xor_b32_e32 v232, v232, v233
	v_lshlrev_b32_e32 v232, 4, v232
	v_lshl_or_b32 v212, v231, 12, v232
	v_lshl_or_b32 v220, v231, 11, v232
	v_xor_b32_e32 v213, 64, v212
	v_add_u32_e32 v213, 0x8000, v213
	v_xor_b32_e32 v221, 64, v220
	v_add_u32_e32 v221, 0x4000, v221
	v_add_u32_e32 v214, 0x10000, v212
	v_add_u32_e32 v222, 0x8000, v220
	v_add_u32_e32 v215, 0x10000, v213
	v_add_u32_e32 v223, 0x8000, v221
	v_add_u32_e32 v216, 0x20000, v212
	v_add_u32_e32 v224, 0x10000, v220
	v_add_u32_e32 v217, 0x20000, v213
	v_add_u32_e32 v225, 0x10000, v221
	v_add_u32_e32 v218, 0x30000, v212
	v_add_u32_e32 v226, 0x18000, v220
	v_add_u32_e32 v219, 0x30000, v213
	v_add_u32_e32 v227, 0x18000, v221
	v_and_b32_e32 v231, 15, v230
	v_lshrrev_b32_e32 v232, 4, v230
	v_lshrrev_b32_e32 v233, 1, v231
	v_xor_b32_e32 v232, v232, v233
	v_lshlrev_b32_e32 v232, 4, v232
	v_lshl_or_b32 v228, v231, 7, v232
	v_lshrrev_b32_e32 v233, 6, v186
	v_lshl_add_u32 v228, v233, 14, v228
	v_xor_b32_e32 v229, 64, v228
	v_lshlrev_b32_e32 v234, 4, v230
	v_lshl_add_u32 v234, v233, 14, v234
.LBB0_60:
	s_and_b32 s5, s6, 0x1c0
	v_readfirstlane_b32 s8, v186
	s_bitset1_b32 s5, 14
	s_ashr_i32 s10, s8, 6
	s_lshl_b32 s8, s10, 7
	s_ashr_i32 s9, s8, 31
	s_lshl_b64 s[8:9], s[8:9], 1
	s_lshl_b32 s4, s7, 3
	s_andn2_b32 s4, s4, 63
	s_lshl_b32 s100, s5, 12
	s_add_u32 s100, s100, s18
	s_addc_u32 s101, s19, 0
	s_add_u32 s100, s100, s8
	s_addc_u32 s101, s101, s9
	s_add_u32 s8, s8, s0
	s_addc_u32 s9, s9, s1
	s_lshl_b32 vcc_lo, s4, 11
	s_add_u32 s8, s8, vcc_lo
	s_addc_u32 s9, s9, 0
	s_lshl_b32 m0, s10, 14
	s_nop 0
	global_load_lds_dwordx4 v212, s[100:101]
	s_add_i32 m0, m0, 0x400
	s_nop 0
	global_load_lds_dwordx4 v213, s[100:101]
	s_add_i32 m0, m0, 0x400
	s_nop 0
	global_load_lds_dwordx4 v214, s[100:101]
	s_add_i32 m0, m0, 0x400
	s_nop 0
	global_load_lds_dwordx4 v215, s[100:101]
	s_add_i32 m0, m0, 0x400
	s_nop 0
	global_load_lds_dwordx4 v216, s[100:101]
	s_add_i32 m0, m0, 0x400
	s_nop 0
	global_load_lds_dwordx4 v217, s[100:101]
	s_add_i32 m0, m0, 0x400
	s_nop 0
	global_load_lds_dwordx4 v218, s[100:101]
	s_add_i32 m0, m0, 0x400
	s_nop 0
	global_load_lds_dwordx4 v219, s[100:101]
	s_add_i32 m0, m0, 0x400
	s_nop 0
	global_load_lds_dwordx4 v220, s[8:9]
	s_add_i32 m0, m0, 0x400
	s_nop 0
	global_load_lds_dwordx4 v221, s[8:9]
	s_add_i32 m0, m0, 0x400
	s_nop 0
	global_load_lds_dwordx4 v222, s[8:9]
	s_add_i32 m0, m0, 0x400
	s_nop 0
	global_load_lds_dwordx4 v223, s[8:9]
	s_add_i32 m0, m0, 0x400
	s_nop 0
	global_load_lds_dwordx4 v224, s[8:9]
	s_add_i32 m0, m0, 0x400
	s_nop 0
	global_load_lds_dwordx4 v225, s[8:9]
	s_add_i32 m0, m0, 0x400
	s_nop 0
	global_load_lds_dwordx4 v226, s[8:9]
	s_add_i32 m0, m0, 0x400
	s_nop 0
	global_load_lds_dwordx4 v227, s[8:9]
	global_load_dwordx4 v[80:83], v212, s[100:101] offset:128
	global_load_dwordx4 v[84:87], v213, s[100:101] offset:128
	global_load_dwordx4 v[88:91], v214, s[100:101] offset:128
	global_load_dwordx4 v[92:95], v215, s[100:101] offset:128
	global_load_dwordx4 v[96:99], v216, s[100:101] offset:128
	global_load_dwordx4 v[100:103], v217, s[100:101] offset:128
	global_load_dwordx4 v[104:107], v218, s[100:101] offset:128
	global_load_dwordx4 v[108:111], v219, s[100:101] offset:128
	global_load_dwordx4 v[112:115], v220, s[8:9] offset:128
	global_load_dwordx4 v[116:119], v221, s[8:9] offset:128
	global_load_dwordx4 v[120:123], v222, s[8:9] offset:128
	global_load_dwordx4 v[124:127], v223, s[8:9] offset:128
	global_load_dwordx4 v[136:139], v224, s[8:9] offset:128
	global_load_dwordx4 v[140:143], v225, s[8:9] offset:128
	global_load_dwordx4 v[144:147], v226, s[8:9] offset:128
	global_load_dwordx4 v[148:151], v227, s[8:9] offset:128
	s_waitcnt vmcnt(16)
	ds_read_b128 v[16:19], v228 offset:0
	ds_read_b128 v[20:23], v229 offset:0
	ds_read_b128 v[24:27], v228 offset:2048
	ds_read_b128 v[28:31], v229 offset:2048
	ds_read_b128 v[32:35], v228 offset:4096
	ds_read_b128 v[36:39], v229 offset:4096
	ds_read_b128 v[40:43], v228 offset:6144
	ds_read_b128 v[44:47], v229 offset:6144
	ds_read_b128 v[48:51], v228 offset:8192
	ds_read_b128 v[52:55], v229 offset:8192
	ds_read_b128 v[56:59], v228 offset:10240
	ds_read_b128 v[60:63], v229 offset:10240
	ds_read_b128 v[64:67], v228 offset:12288
	ds_read_b128 v[68:71], v229 offset:12288
	ds_read_b128 v[72:75], v228 offset:14336
	ds_read_b128 v[76:79], v229 offset:14336
	s_waitcnt lgkmcnt(0)
	s_waitcnt vmcnt(0)
; template <int NT, int ACT, int K>
; __device__ __forceinline__ void small_gemm_tile(LAS unsigned char* lds, const bf16* __restrict__ A, const bf16* __restrict__ Bt, bf16* __restrict__ O, int ldc, int lda, int ldb, const float* __restrict__ rs, int m0, int n0, int tid) {
;     ...
;     if constexpr (NCH == 1) {
;         bf16x8 fa[4][4], fb[4][NT];
; #pragma unroll
;         for (int s_ = 0; s_ < 4; ++s_) {
; #pragma unroll
;             for (int m = 0; m < 4; ++m) fa[s_][m] = *(const bf16x8*)(ap + (size_t)m * 16 * lda + s_ * 32);
; #pragma unroll
;             for (int n = 0; n < NT; ++n) fb[s_][n] = *(const bf16x8*)(bp + (size_t)n * 16 * ldb + s_ * 32); }
;         __builtin_amdgcn_sched_barrier(0);
; #pragma unroll
;         for (int s_ = 0; s_ < 4; ++s_)
; #pragma unroll
;             for (int m = 0; m < 4; ++m)
; #pragma unroll
;                 for (int n = 0; n < NT; ++n) acc[m][n] = __builtin_amdgcn_mfma_f32_16x16x32_bf16(fa[s_][m], fb[s_][n], acc[m][n], 0, 0, 0);
;         __builtin_amdgcn_sched_barrier(0);
	ds_write_b128 v234, v[80:83]
	ds_write_b128 v234, v[84:87] offset:1024
	ds_write_b128 v234, v[88:91] offset:2048
	ds_write_b128 v234, v[92:95] offset:3072
	ds_write_b128 v234, v[96:99] offset:4096
	ds_write_b128 v234, v[100:103] offset:5120
	ds_write_b128 v234, v[104:107] offset:6144
	ds_write_b128 v234, v[108:111] offset:7168
	ds_write_b128 v234, v[112:115] offset:8192
	ds_write_b128 v234, v[116:119] offset:9216
	ds_write_b128 v234, v[120:123] offset:10240
	ds_write_b128 v234, v[124:127] offset:11264
	ds_write_b128 v234, v[136:139] offset:12288
	ds_write_b128 v234, v[140:143] offset:13312
	ds_write_b128 v234, v[144:147] offset:14336
	ds_write_b128 v234, v[148:151] offset:15360
	v_mfma_f32_16x16x32_bf16 v[154:157], v[16:19], v[48:51], 0
	v_mfma_f32_16x16x32_bf16 v[158:161], v[16:19], v[56:59], 0
	v_mfma_f32_16x16x32_bf16 v[162:165], v[16:19], v[64:67], 0
	v_mfma_f32_16x16x32_bf16 v[16:19], v[16:19], v[72:75], 0
	v_mfma_f32_16x16x32_bf16 v[188:191], v[24:27], v[48:51], 0
	v_mfma_f32_16x16x32_bf16 v[192:195], v[24:27], v[56:59], 0
	v_mfma_f32_16x16x32_bf16 v[196:199], v[24:27], v[64:67], 0
	v_mfma_f32_16x16x32_bf16 v[24:27], v[24:27], v[72:75], 0
	v_mfma_f32_16x16x32_bf16 v[200:203], v[32:35], v[48:51], 0
	v_mfma_f32_16x16x32_bf16 v[204:207], v[32:35], v[56:59], 0
	v_mfma_f32_16x16x32_bf16 v[208:211], v[32:35], v[64:67], 0
	v_mfma_f32_16x16x32_bf16 v[32:35], v[32:35], v[72:75], 0
	v_mfma_f32_16x16x32_bf16 v[48:51], v[40:43], v[48:51], 0
	v_mfma_f32_16x16x32_bf16 v[56:59], v[40:43], v[56:59], 0
	v_mfma_f32_16x16x32_bf16 v[64:67], v[40:43], v[64:67], 0
	v_mfma_f32_16x16x32_bf16 v[40:43], v[40:43], v[72:75], 0
	v_mfma_f32_16x16x32_bf16 v[72:75], v[20:23], v[52:55], v[154:157]
	v_mfma_f32_16x16x32_bf16 v[154:157], v[20:23], v[60:63], v[158:161]
	v_mfma_f32_16x16x32_bf16 v[158:161], v[20:23], v[68:71], v[162:165]
	v_mfma_f32_16x16x32_bf16 v[16:19], v[20:23], v[76:79], v[16:19]
	v_mfma_f32_16x16x32_bf16 v[20:23], v[28:31], v[52:55], v[188:191]
	v_mfma_f32_16x16x32_bf16 v[162:165], v[28:31], v[60:63], v[192:195]
	v_mfma_f32_16x16x32_bf16 v[188:191], v[28:31], v[68:71], v[196:199]
	v_mfma_f32_16x16x32_bf16 v[24:27], v[28:31], v[76:79], v[24:27]
	v_mfma_f32_16x16x32_bf16 v[28:31], v[36:39], v[52:55], v[200:203]
	v_mfma_f32_16x16x32_bf16 v[192:195], v[36:39], v[60:63], v[204:207]
	v_mfma_f32_16x16x32_bf16 v[196:199], v[36:39], v[68:71], v[208:211]
	v_mfma_f32_16x16x32_bf16 v[32:35], v[36:39], v[76:79], v[32:35]
	v_mfma_f32_16x16x32_bf16 v[36:39], v[44:47], v[52:55], v[48:51]
	v_mfma_f32_16x16x32_bf16 v[48:51], v[44:47], v[60:63], v[56:59]
	v_mfma_f32_16x16x32_bf16 v[52:55], v[44:47], v[68:71], v[64:67]
	v_mfma_f32_16x16x32_bf16 v[40:43], v[44:47], v[76:79], v[40:43]
	s_waitcnt lgkmcnt(0)
	ds_read_b128 v[80:83], v228 offset:0
	ds_read_b128 v[84:87], v229 offset:0
	ds_read_b128 v[88:91], v228 offset:2048
	ds_read_b128 v[92:95], v229 offset:2048
	ds_read_b128 v[96:99], v228 offset:4096
	ds_read_b128 v[100:103], v229 offset:4096
	ds_read_b128 v[104:107], v228 offset:6144
	ds_read_b128 v[108:111], v229 offset:6144
	ds_read_b128 v[112:115], v228 offset:8192
	ds_read_b128 v[116:119], v229 offset:8192
	ds_read_b128 v[120:123], v228 offset:10240
	ds_read_b128 v[124:127], v229 offset:10240
	ds_read_b128 v[136:139], v228 offset:12288
	ds_read_b128 v[140:143], v229 offset:12288
	ds_read_b128 v[144:147], v228 offset:14336
	ds_read_b128 v[148:151], v229 offset:14336
	s_waitcnt lgkmcnt(0)
	v_mfma_f32_16x16x32_bf16 v[44:47], v[80:83], v[112:115], v[72:75]
	v_mfma_f32_16x16x32_bf16 v[56:59], v[80:83], v[120:123], v[154:157]
	v_mfma_f32_16x16x32_bf16 v[60:63], v[80:83], v[136:139], v[158:161]
	v_mfma_f32_16x16x32_bf16 v[16:19], v[80:83], v[144:147], v[16:19]
	v_mfma_f32_16x16x32_bf16 v[20:23], v[88:91], v[112:115], v[20:23]
	v_mfma_f32_16x16x32_bf16 v[64:67], v[88:91], v[120:123], v[162:165]
	v_mfma_f32_16x16x32_bf16 v[68:71], v[88:91], v[136:139], v[188:191]
	v_mfma_f32_16x16x32_bf16 v[24:27], v[88:91], v[144:147], v[24:27]
	v_mfma_f32_16x16x32_bf16 v[28:31], v[96:99], v[112:115], v[28:31]
	v_mfma_f32_16x16x32_bf16 v[72:75], v[96:99], v[120:123], v[192:195]
	v_mfma_f32_16x16x32_bf16 v[76:79], v[96:99], v[136:139], v[196:199]
	v_mfma_f32_16x16x32_bf16 v[32:35], v[96:99], v[144:147], v[32:35]
	v_mfma_f32_16x16x32_bf16 v[36:39], v[104:107], v[112:115], v[36:39]
	v_mfma_f32_16x16x32_bf16 v[48:51], v[104:107], v[120:123], v[48:51]
	v_mfma_f32_16x16x32_bf16 v[52:55], v[104:107], v[136:139], v[52:55]
	v_mfma_f32_16x16x32_bf16 v[40:43], v[104:107], v[144:147], v[40:43]
	v_mfma_f32_16x16x32_bf16 v[44:47], v[84:87], v[116:119], v[44:47]
	v_mfma_f32_16x16x32_bf16 v[56:59], v[84:87], v[124:127], v[56:59]
	v_mfma_f32_16x16x32_bf16 v[60:63], v[84:87], v[140:143], v[60:63]
	v_mfma_f32_16x16x32_bf16 v[16:19], v[84:87], v[148:151], v[16:19]
	v_mfma_f32_16x16x32_bf16 v[20:23], v[92:95], v[116:119], v[20:23]
	v_mfma_f32_16x16x32_bf16 v[64:67], v[92:95], v[124:127], v[64:67]
	v_mfma_f32_16x16x32_bf16 v[68:71], v[92:95], v[140:143], v[68:71]
	v_mfma_f32_16x16x32_bf16 v[24:27], v[92:95], v[148:151], v[24:27]
	v_mfma_f32_16x16x32_bf16 v[28:31], v[100:103], v[116:119], v[28:31]
	v_mfma_f32_16x16x32_bf16 v[72:75], v[100:103], v[124:127], v[72:75]
	v_mfma_f32_16x16x32_bf16 v[76:79], v[100:103], v[140:143], v[76:79]
	v_mfma_f32_16x16x32_bf16 v[32:35], v[100:103], v[148:151], v[32:35]
	v_mfma_f32_16x16x32_bf16 v[36:39], v[108:111], v[116:119], v[36:39]
	v_mfma_f32_16x16x32_bf16 v[48:51], v[108:111], v[124:127], v[48:51]
	v_mfma_f32_16x16x32_bf16 v[52:55], v[108:111], v[140:143], v[52:55]
	v_mfma_f32_16x16x32_bf16 v[40:43], v[108:111], v[148:151], v[40:43]
	v_lshl_add_u32 v3, s10, 14, v14
; #define LAS __attribute__((address_space(3)))
; __device__ __forceinline__ unsigned pk2(float lo, float hi) { return f2bf(lo) | (f2bf(hi) << 16); }
; template <int NT, int ACT, int K>
; __device__ __forceinline__ void small_gemm_tile(LAS unsigned char* lds, const bf16* __restrict__ A, const bf16* __restrict__ Bt, bf16* __restrict__ O, int ldc, int lda, int ldb, const float* __restrict__ rs, int m0, int n0, int tid) {
;     ...
;     LAS float* P = (LAS float*)lds + wave * (64 * NC);
; #pragma unroll
;     for (int m = 0; m < 4; ++m)
; #pragma unroll
;         for (int n = 0; n < NT; ++n)
; #pragma unroll
;             for (int i = 0; i < 4; ++i) P[(m * 16 + fq * 4 + i) * NC + n * 16 + fr] = acc[m][n][i];
;     __syncthreads();
;     constexpr int EPT = 64 * NC / 512;
;     const int e0 = tid * EPT, row = e0 / NC, col = e0 % NC;
;     float r[EPT];
; #pragma unroll
;     for (int j = 0; j < EPT; ++j) r[j] = 0.f;
; #pragma unroll
;     for (int w = 0; w < 8; ++w) { const LAS f32x4* q = (const LAS f32x4*)((LAS float*)lds + w * (64 * NC) + e0);
; #pragma unroll
;         for (int j = 0; j < EPT / 4; ++j) { const f32x4 v = q[j]; r[4 * j] += v[0]; r[4 * j + 1] += v[1]; r[4 * j + 2] += v[2]; r[4 * j + 3] += v[3]; } }
;     if (rs) { const float sc = rs[m0 + row];
; #pragma unroll
;         for (int j = 0; j < EPT; ++j) r[j] *= sc; }
;     if (ACT == 1) {
; #pragma unroll
;         for (int j = 0; j < EPT; ++j) { const float t = fmaxf(r[j], 0.f); r[j] = t * t; } }
;     bf16* op = O + (size_t)(m0 + row) * ldc + n0 + col;
;     if (EPT == 8) { v4u w; w.x = pk2(r[0], r[1]); w.y = pk2(r[2], r[3]); w.z = pk2(r[4 % EPT], r[5 % EPT]); w.w = pk2(r[6 % EPT], r[7 % EPT]); *(v4u*)op = w; }
;     else { v2u w; w.x = pk2(r[0], r[1]); w.y = pk2(r[2], r[3]); *(v2u*)op = w; }
;     __syncthreads();
	v_add_u32_e32 v15, 0x1000, v3
	ds_write2_b32 v3, v44, v56 offset1:16
	ds_write2_b32 v3, v45, v57 offset0:64 offset1:80
	ds_write2_b32 v3, v46, v58 offset0:128 offset1:144
	ds_write2_b32 v3, v47, v59 offset0:192 offset1:208
	ds_write2_b32 v3, v60, v16 offset0:32 offset1:48
	ds_write2_b32 v3, v61, v17 offset0:96 offset1:112
	ds_write2_b32 v3, v62, v18 offset0:160 offset1:176
	ds_write2_b32 v3, v63, v19 offset0:224 offset1:240
	ds_write2_b32 v15, v20, v64 offset1:16
	ds_write2_b32 v15, v21, v65 offset0:64 offset1:80
	ds_write2_b32 v15, v22, v66 offset0:128 offset1:144
	ds_write2_b32 v15, v23, v67 offset0:192 offset1:208
	ds_write2_b32 v15, v68, v24 offset0:32 offset1:48
	ds_write2_b32 v15, v69, v25 offset0:96 offset1:112
	ds_write2_b32 v15, v70, v26 offset0:160 offset1:176
	ds_write2_b32 v15, v71, v27 offset0:224 offset1:240
	v_add_u32_e32 v24, s5, v13
	v_ashrrev_i32_e32 v25, 31, v24
	v_add_u32_e32 v15, 0x2000, v3
	v_add_u32_e32 v3, 0x3000, v3
	v_lshl_add_u64 v[20:21], v[24:25], 2, s[82:83]
	ds_write2_b32 v15, v28, v72 offset1:16
	ds_write2_b32 v15, v29, v73 offset0:64 offset1:80
	ds_write2_b32 v15, v30, v74 offset0:128 offset1:144
	ds_write2_b32 v15, v31, v75 offset0:192 offset1:208
	ds_write2_b32 v15, v76, v32 offset0:32 offset1:48
	ds_write2_b32 v15, v77, v33 offset0:96 offset1:112
	ds_write2_b32 v15, v78, v34 offset0:160 offset1:176
	ds_write2_b32 v15, v79, v35 offset0:224 offset1:240
	ds_write2_b32 v3, v36, v48 offset1:16
	ds_write2_b32 v3, v37, v49 offset0:64 offset1:80
	ds_write2_b32 v3, v38, v50 offset0:128 offset1:144
	ds_write2_b32 v3, v39, v51 offset0:192 offset1:208
	ds_write2_b32 v3, v52, v40 offset0:32 offset1:48
	ds_write2_b32 v3, v53, v41 offset0:96 offset1:112
	ds_write2_b32 v3, v54, v42 offset0:160 offset1:176
	ds_write2_b32 v3, v55, v43 offset0:224 offset1:240
	s_waitcnt lgkmcnt(0)
	s_barrier
	global_load_dword v3, v[20:21], off
	ds_read_b128 v[16:19], v4
	ds_read_b128 v[20:23], v4 offset:16
	s_movk_i32 s5, 0x2080
	s_add_i32 s7, s7, s3
	s_add_i32 s6, s6, s2
	s_waitcnt lgkmcnt(1)
	v_add_f32_e32 v15, 0, v16
	v_add_f32_e32 v25, 0, v17
	v_add_f32_e32 v26, 0, v18
	v_add_f32_e32 v27, 0, v19
	s_waitcnt lgkmcnt(0)
	v_add_f32_e32 v28, 0, v20
	ds_read_b128 v[16:19], v4 offset:16384
	v_add_f32_e32 v29, 0, v21
	v_add_f32_e32 v30, 0, v22
	v_add_f32_e32 v31, 0, v23
	ds_read_b128 v[20:23], v4 offset:16400
	s_waitcnt lgkmcnt(1)
	v_add_f32_e32 v15, v15, v16
	v_add_f32_e32 v25, v25, v17
	v_add_f32_e32 v26, v26, v18
	v_add_f32_e32 v27, v27, v19
	s_waitcnt lgkmcnt(0)
	v_add_f32_e32 v28, v28, v20
	ds_read_b128 v[16:19], v4 offset:32768
	v_add_f32_e32 v29, v29, v21
	v_add_f32_e32 v30, v30, v22
	v_add_f32_e32 v31, v31, v23
	ds_read_b128 v[20:23], v4 offset:32784
	s_waitcnt lgkmcnt(1)
	v_add_f32_e32 v15, v15, v16
	v_add_f32_e32 v25, v25, v17
	v_add_f32_e32 v26, v26, v18
	v_add_f32_e32 v27, v27, v19
	s_waitcnt lgkmcnt(0)
	v_add_f32_e32 v28, v28, v20
	ds_read_b128 v[16:19], v4 offset:49152
	v_add_f32_e32 v29, v29, v21
	v_add_f32_e32 v30, v30, v22
	v_add_f32_e32 v31, v31, v23
	ds_read_b128 v[20:23], v4 offset:49168
	s_waitcnt lgkmcnt(1)
	v_add_f32_e32 v15, v15, v16
	v_add_f32_e32 v25, v25, v17
	v_add_f32_e32 v26, v26, v18
	v_add_f32_e32 v27, v27, v19
	s_waitcnt lgkmcnt(0)
	v_add_f32_e32 v28, v28, v20
	ds_read_b128 v[16:19], v5
	v_add_f32_e32 v29, v29, v21
	v_add_f32_e32 v30, v30, v22
	v_add_f32_e32 v31, v31, v23
	ds_read_b128 v[20:23], v6
	s_waitcnt lgkmcnt(1)
	v_add_f32_e32 v15, v15, v16
	v_add_f32_e32 v25, v25, v17
	v_add_f32_e32 v26, v26, v18
	v_add_f32_e32 v27, v27, v19
	s_waitcnt lgkmcnt(0)
	v_add_f32_e32 v28, v28, v20
	ds_read_b128 v[16:19], v7
	v_add_f32_e32 v29, v29, v21
	v_add_f32_e32 v30, v30, v22
	v_add_f32_e32 v31, v31, v23
	ds_read_b128 v[20:23], v8
	s_waitcnt lgkmcnt(1)
	v_add_f32_e32 v15, v15, v16
	v_add_f32_e32 v25, v25, v17
	v_add_f32_e32 v26, v26, v18
	v_add_f32_e32 v27, v27, v19
	s_waitcnt lgkmcnt(0)
	v_add_f32_e32 v28, v28, v20
	ds_read_b128 v[16:19], v9
	v_add_f32_e32 v29, v29, v21
	v_add_f32_e32 v30, v30, v22
	v_add_f32_e32 v31, v31, v23
	ds_read_b128 v[20:23], v10
	s_waitcnt lgkmcnt(1)
	v_add_f32_e32 v15, v15, v16
	v_add_f32_e32 v25, v25, v17
	v_add_f32_e32 v26, v26, v18
	v_add_f32_e32 v27, v27, v19
	s_waitcnt lgkmcnt(0)
	v_add_f32_e32 v28, v28, v20
	ds_read_b128 v[16:19], v11
	v_add_f32_e32 v29, v29, v21
	v_add_f32_e32 v30, v30, v22
	v_add_f32_e32 v31, v31, v23
	ds_read_b128 v[20:23], v12
	s_waitcnt lgkmcnt(1)
	v_add_f32_e32 v15, v15, v16
	v_add_f32_e32 v16, v25, v17
	v_add_f32_e32 v17, v26, v18
	v_add_f32_e32 v18, v27, v19
	s_waitcnt lgkmcnt(0)
	v_add_f32_e32 v19, v28, v20
	v_add_f32_e32 v20, v29, v21
	v_add_f32_e32 v21, v30, v22
	v_add_f32_e32 v22, v31, v23
	s_waitcnt vmcnt(0)
	v_mul_f32_e32 v15, v3, v15
	v_mul_f32_e32 v23, v3, v16
	v_mul_f32_e32 v17, v3, v17
	v_mul_f32_e32 v25, v3, v18
	v_mul_f32_e32 v26, v3, v19
	v_mul_f32_e32 v27, v3, v20
	v_mul_f32_e32 v21, v3, v21
	v_mul_f32_e32 v3, v3, v22
	v_max_f32_e32 v18, 0, v23
	v_max_f32_e32 v19, 0, v25
	v_max_f32_e32 v22, 0, v27
	v_max_f32_e32 v23, 0, v3
	v_max_f32_e32 v16, 0, v15
	v_max_f32_e32 v17, 0, v17
	v_max_f32_e32 v20, 0, v26
	v_max_f32_e32 v21, 0, v21
	v_mov_b64_e32 v[26:27], s[64:65]
	v_pk_mul_f32 v[18:19], v[18:19], v[18:19]
	v_pk_mul_f32 v[22:23], v[22:23], v[22:23]
	v_mad_i64_i32 v[24:25], s[8:9], v24, s5, v[26:27]
	v_pk_mul_f32 v[16:17], v[16:17], v[16:17]
	v_pk_mul_f32 v[20:21], v[20:21], v[20:21]
	v_bfe_u32 v3, v23, 16, 1
	v_bfe_u32 v15, v22, 16, 1
	v_bfe_u32 v26, v19, 16, 1
	v_bfe_u32 v27, v18, 16, 1
	v_add3_u32 v27, v18, v27, s90
	v_add3_u32 v26, v19, v26, s90
	v_add3_u32 v15, v22, v15, s90
	v_add3_u32 v3, v23, v3, s90
	v_bfe_u32 v18, v16, 16, 1
	v_bfe_u32 v19, v17, 16, 1
	v_bfe_u32 v22, v20, 16, 1
	v_bfe_u32 v23, v21, 16, 1
	s_ashr_i32 s5, s4, 31
	v_add3_u32 v21, v21, v23, s90
	v_add3_u32 v20, v20, v22, s90
	v_add3_u32 v17, v17, v19, s90
	v_add3_u32 v16, v16, v18, s90
	v_lshl_add_u64 v[24:25], s[4:5], 1, v[24:25]
	v_lshrrev_b32_e32 v16, 16, v16
	v_lshrrev_b32_e32 v17, 16, v17
	v_lshrrev_b32_e32 v18, 16, v20
	v_lshrrev_b32_e32 v19, 16, v21
	v_lshl_add_u64 v[24:25], v[0:1], 1, v[24:25]
	v_and_or_b32 v19, v3, s91, v19
	v_and_or_b32 v18, v15, s91, v18
	v_and_or_b32 v17, v26, s91, v17
	v_and_or_b32 v16, v27, s91, v16
	s_cmpk_gt_i32 s7, 0x1ff
	global_store_dwordx4 v[24:25], v[16:19], off
	s_barrier
	s_cbranch_scc0 .LBB0_60

;     __device__ __forceinline__ void operator()(const f32x4 (&acc)[2][2][4][2], const Unit& u, int wr, int wc, int fr, int fq) const {
;         const int row0 = u.pm * BM + wr * 64 + fr; const int col0 = u.pn * BM + wc * 32 + 8 * fq;
; #pragma unroll
;         for (int ai = 0; ai < 2; ++ai)
; #pragma unroll
;             for (int m = 0; m < 4; ++m) { const int row_ = row0 + ai * HALF + m * 16; bf16_t* rowp = O + (size_t)(row_ >> 11) * gs + (size_t)(row_ & 2047) * ldc + col0; const float sc = rs ? rs[row0 + ai * HALF + m * 16] : 1.f;
.LBB0_459:
	s_lshl_b32 vcc_lo, s41, 8
	s_add_i32 vcc_lo, vcc_lo, s31
	v_or_b32_e32 v152, vcc_lo, v153
	v_lshlrev_b32_e32 v152, 2, v152
	s_and_b64 vcc, exec, s[68:69]
	s_cbranch_vccz .Lrsh_pl_nors
	global_load_dword v154, v152, s[82:83]
	global_load_dword v187, v152, s[82:83] offset:64
	global_load_dword v169, v152, s[82:83] offset:128
	global_load_dword v170, v152, s[82:83] offset:192
	global_load_dword v172, v152, s[82:83] offset:512
	global_load_dword v173, v152, s[82:83] offset:576
	global_load_dword v174, v152, s[82:83] offset:640
	global_load_dword v152, v152, s[82:83] offset:704
	s_branch .Lrsh_pl_go
.Lrsh_pl_nors:
	v_mov_b32_e32 v154, 1.0
	v_mov_b32_e32 v187, 1.0
	v_mov_b32_e32 v169, 1.0
	v_mov_b32_e32 v170, 1.0
	v_mov_b32_e32 v172, 1.0
	v_mov_b32_e32 v173, 1.0
	v_mov_b32_e32 v174, 1.0
	v_mov_b32_e32 v152, 1.0

;     __device__ __forceinline__ void operator()(const f32x4 (&acc)[2][2][4][2], const Unit& u, int wr, int wc, int fr, int fq) const {
;         const int row0 = u.pm * BM + wr * 64 + fr; const int col0 = u.pn * BM + wc * 32 + 8 * fq;
; #pragma unroll
;         for (int ai = 0; ai < 2; ++ai)
; #pragma unroll
;             for (int m = 0; m < 4; ++m) { const int row_ = row0 + ai * HALF + m * 16; bf16_t* rowp = O + (size_t)(row_ >> 11) * gs + (size_t)(row_ & 2047) * ldc + col0; const float sc = rs ? rs[row0 + ai * HALF + m * 16] : 1.f;
.LBB0_471:
	s_lshl_b32 s41, s41, 8
	s_add_i32 s41, s41, s31
	v_or_b32_e32 v150, s41, v153
	s_waitcnt vmcnt(16)
	v_mov_b32_e32 v200, v154
	v_mov_b32_e32 v202, v187
	v_mov_b32_e32 v204, v169
	v_mov_b32_e32 v206, v170
	v_mov_b32_e32 v208, v172
	v_mov_b32_e32 v210, v173
	v_mov_b32_e32 v212, v174
	v_mov_b32_e32 v214, v152
	v_mov_b32_e32 v169, 0x1000
	v_mov_b32_e32 v170, 0x2000
	v_mov_b32_e32 v172, 0x82000
	v_mov_b32_e32 v173, 0xffffef80
	v_mov_b32_e32 v174, 0xfffff800

; __device__ __forceinline__ unsigned cvt_pk_bf16(float lo, float hi) { unsigned r; asm volatile("v_cvt_pk_bf16_f32 %0, %1, %2" : "=v"(r) : "v"(lo), "v"(hi)); return r; }
; __device__ __forceinline__ float relu_sq(float x) { float r; asm volatile("v_max_f32 %0, 0, %1" : "=v"(r) : "v"(x)); return r * r; }
;     __device__ __forceinline__ void operator()(const f32x4 (&acc)[2][2][4][2], const Unit& u, int wr, int wc, int fr, int fq) const {
;     ...
;             for (int m = 0; m < 4; ++m) { const int row_ = row0 + ai * HALF + m * 16; bf16_t* rowp = O + (size_t)(row_ >> 11) * gs + (size_t)(row_ & 2047) * ldc + col0; const float sc = rs ? rs[row0 + ai * HALF + m * 16] : 1.f;
; #pragma unroll
;                 for (int bj = 0; bj < 2; ++bj) { f32x4 v0 = acc[ai][bj][m][0] * sc, v1 = acc[ai][bj][m][1] * sc;
;                     if (ACT == 1) {
; #pragma unroll
;                         for (int e = 0; e < 4; ++e) { v0[e] = relu_sq(v0[e]); v1[e] = relu_sq(v1[e]); } }
;                     u32x4 w; w.x = cvt_pk_bf16(v0[0], v0[1]); w.y = cvt_pk_bf16(v0[2], v0[3]); w.z = cvt_pk_bf16(v1[0], v1[1]); w.w = cvt_pk_bf16(v1[2], v1[3]);
;                     *(u32x4*)(rowp + bj * HALF) = w; } }
.LBB0_473:
	v_bitop3_b32 v128, v150, v184, v150 bitop3:0xc8
	s_ashr_i32 s41, s41, 11
	s_mul_hi_i32 s43, s26, s41
	s_mul_i32 s42, s26, s41
	s_lshl_b64 s[42:43], s[42:43], 1
	v_lshl_or_b32 v148, s88, 8, v152
	s_add_u32 s88, s12, s42
	v_mul_u32_u24_e32 v128, s39, v128
	s_addc_u32 s89, s13, s43
	v_lshlrev_b32_e32 v128, 1, v128
	v_ashrrev_i32_e32 v149, 31, v148
	v_lshl_add_u64 v[158:159], s[88:89], 0, v[128:129]
	v_lshl_add_u64 v[158:159], v[148:149], 1, v[158:159]
	s_nop 0
	v_pk_mul_f32 v[126:127], v[126:127], v[200:201] op_sel_hi:[1,0]
	v_pk_mul_f32 v[124:125], v[124:125], v[200:201] op_sel_hi:[1,0]
	v_pk_mul_f32 v[160:161], v[122:123], v[200:201] op_sel_hi:[1,0]
	v_pk_mul_f32 v[122:123], v[120:121], v[200:201] op_sel_hi:[1,0]
	v_cvt_pk_bf16_f32 v120, v124, v125
	v_cvt_pk_bf16_f32 v121, v126, v127
	s_nop 0
	v_cvt_pk_bf16_f32 v122, v122, v123
	v_cvt_pk_bf16_f32 v123, v160, v161
	ds_write_b128 v154, v[120:123]
	ds_read_b128 v[216:219], v187
	s_nop 1
	v_pk_mul_f32 v[118:119], v[118:119], v[200:201] op_sel_hi:[1,0]
	v_pk_mul_f32 v[116:117], v[116:117], v[200:201] op_sel_hi:[1,0]
	v_pk_mul_f32 v[120:121], v[114:115], v[200:201] op_sel_hi:[1,0]
	v_pk_mul_f32 v[114:115], v[112:113], v[200:201] op_sel_hi:[1,0]
	v_cvt_pk_bf16_f32 v112, v116, v117
	v_cvt_pk_bf16_f32 v113, v118, v119
	s_nop 0
	v_cvt_pk_bf16_f32 v114, v114, v115
	v_cvt_pk_bf16_f32 v115, v120, v121
	s_waitcnt lgkmcnt(0)
	global_store_dwordx4 v[158:159], v[216:219], off
	ds_write_b128 v154, v[112:115]
	ds_read_b128 v[216:219], v187
	s_nop 1
	s_nop 0

; template <int NT, int ACT, int K>
; __device__ __forceinline__ void small_gemm_tile(LAS unsigned char* lds, const bf16* __restrict__ A, const bf16* __restrict__ Bt, bf16* __restrict__ O, int ldc, int lda, int ldb, const float* __restrict__ rs, int m0, int n0, int tid) {
;     constexpr int NC = 16 * NT, KW = K / 8, NCH = KW / 128;
;     const int wave = __builtin_amdgcn_readfirstlane(tid >> 6), lane = tid & 63, fr = lane & 15, fq = lane >> 4;
;     const bf16* ap = A + (size_t)(m0 + fr) * lda + wave * KW + fq * 8;
;     const bf16* bp = Bt + (size_t)(n0 + fr) * ldb + wave * KW + fq * 8;
;     f32x4 acc[4][NT];
; #pragma unroll
;     for (int m = 0; m < 4; ++m)
; #pragma unroll
;         for (int n = 0; n < NT; ++n) acc[m][n] = (f32x4){0.f, 0.f, 0.f, 0.f};
;     if constexpr (NCH == 1) {
;         bf16x8 fa[4][4], fb[4][NT];
; #pragma unroll
;         for (int s_ = 0; s_ < 4; ++s_) {
; #pragma unroll
;             for (int m = 0; m < 4; ++m) fa[s_][m] = *(const bf16x8*)(ap + (size_t)m * 16 * lda + s_ * 32);
; #pragma unroll
;             for (int n = 0; n < NT; ++n) fb[s_][n] = *(const bf16x8*)(bp + (size_t)n * 16 * ldb + s_ * 32); }
;         __builtin_amdgcn_sched_barrier(0);
; #pragma unroll
;         for (int s_ = 0; s_ < 4; ++s_)
; #pragma unroll
;             for (int m = 0; m < 4; ++m)
; #pragma unroll
;                 for (int n = 0; n < NT; ++n) acc[m][n] = __builtin_amdgcn_mfma_f32_16x16x32_bf16(fa[s_][m], fb[s_][n], acc[m][n], 0, 0, 0);
;         __builtin_amdgcn_sched_barrier(0);
.Lws_nc_pl:
	v_readlane_b32 s6, v253, 30
	v_readlane_b32 s7, v253, 31
	s_waitcnt vmcnt(2)
	v_lshl_add_u32 v4, v153, 2, 0
	s_mov_b64 s[8:9], -1
	s_waitcnt vmcnt(0)
	v_cndmask_b32_e64 v0, 0, 1, s[6:7]
	s_andn2_b64 vcc, exec, s[58:59]
	v_cmp_ne_u32_e64 s[6:7], 1, v0
	s_mov_b64 s[64:65], s[52:53]
	s_mov_b32 s37, 0x18000
	s_mov_b32 s57, 0x8000
	s_mov_b32 s58, 0x20000
	s_mov_b32 s59, 0x30000
	s_mov_b32 s68, s54
	s_mov_b32 s69, s55
	v_readlane_b32 s70, v254, 58
	s_cbranch_vccnz .LBB0_498
	v_readlane_b32 s40, v253, 57
	s_and_b64 vcc, exec, s[6:7]
	v_readlane_b32 s54, v254, 7
	v_readlane_b32 s55, v254, 8
	v_readlane_b32 s41, v253, 58
	v_readlane_b32 s42, v253, 59
	v_readlane_b32 s43, v253, 60
	v_readlane_b32 s44, v253, 61
	v_readlane_b32 s45, v253, 62
	v_readlane_b32 s46, v253, 63
	v_readlane_b32 s47, v254, 0
	v_readlane_b32 s48, v254, 1
	v_readlane_b32 s49, v254, 2
	v_readlane_b32 s50, v254, 3
	v_readlane_b32 s51, v254, 4
	v_readlane_b32 s52, v254, 5
	v_readlane_b32 s53, v254, 6
	s_cbranch_vccnz .LBB0_497
	v_ashrrev_i32_e32 v1, 31, v186
	v_lshrrev_b32_e32 v1, 29, v1
	v_add_u32_e32 v1, v186, v1
	s_waitcnt vmcnt(0)
	v_ashrrev_i32_e32 v14, 3, v1
	v_bfe_i32 v1, v186, 28, 1
	v_lshlrev_b32_e32 v0, 3, v186
	v_lshrrev_b32_e32 v1, 26, v1
	v_add_u32_e32 v1, v0, v1
	v_bfe_u32 v3, v186, 4, 2
	v_and_b32_e32 v1, 0xffffffc0, v1
	v_lshlrev_b32_e32 v2, 3, v3
	v_lshl_add_u32 v5, v186, 5, 0
	v_sub_u32_e32 v0, v0, v1
	v_add_u32_e32 v6, 0x10000, v5
	v_add_u32_e32 v7, 0x10010, v5
	v_add_u32_e32 v8, 0x14000, v5
	v_add_u32_e32 v9, 0x14010, v5
	v_add_u32_e32 v10, 0x18000, v5
	v_add_u32_e32 v11, 0x18010, v5
	v_add_u32_e32 v12, 0x1c000, v5
	v_add_u32_e32 v13, 0x1c010, v5
	v_ashrrev_i32_e32 v1, 31, v0
	v_lshl_add_u32 v15, v3, 10, v4
	v_lshlrev_b32_e32 v2, 1, v2
	s_mov_b32 s2, s60
	v_and_b32_e32 v230, 63, v186
	v_lshrrev_b32_e32 v231, 3, v230
	v_and_b32_e32 v232, 7, v230
	v_lshrrev_b32_e32 v233, 1, v231
	v_xor_b32_e32 v232, v232, v233
	v_lshlrev_b32_e32 v232, 4, v232
	v_lshl_or_b32 v212, v231, 12, v232
	v_lshl_or_b32 v220, v231, 11, v232
	v_xor_b32_e32 v213, 64, v212
	v_add_u32_e32 v213, 0x8000, v213
	v_xor_b32_e32 v221, 64, v220
	v_add_u32_e32 v221, 0x4000, v221
	v_add_u32_e32 v214, 0x10000, v212
	v_add_u32_e32 v222, 0x8000, v220
	v_add_u32_e32 v215, 0x10000, v213
	v_add_u32_e32 v223, 0x8000, v221
	v_add_u32_e32 v216, 0x20000, v212
	v_add_u32_e32 v224, 0x10000, v220
	v_add_u32_e32 v217, 0x20000, v213
	v_add_u32_e32 v225, 0x10000, v221
	v_add_u32_e32 v218, 0x30000, v212
	v_add_u32_e32 v226, 0x18000, v220
	v_add_u32_e32 v219, 0x30000, v213
	v_add_u32_e32 v227, 0x18000, v221
	v_and_b32_e32 v231, 15, v230
	v_lshrrev_b32_e32 v232, 4, v230
	v_lshrrev_b32_e32 v233, 1, v231
	v_xor_b32_e32 v232, v232, v233
	v_lshlrev_b32_e32 v232, 4, v232
	v_lshl_or_b32 v228, v231, 7, v232
	v_lshrrev_b32_e32 v233, 6, v186
	v_lshl_add_u32 v228, v233, 14, v228
	v_xor_b32_e32 v229, 64, v228
	v_lshlrev_b32_e32 v234, 4, v230
	v_lshl_add_u32 v234, v233, 14, v234
.LBB0_496:
	s_and_b32 s8, s2, 7
	s_mul_i32 s9, s8, 0x82000
	s_add_u32 s9, s62, s9
	s_addc_u32 s14, s63, 0
	s_lshl_b32 s15, s8, 6
	s_bitset1_b32 s15, 14
	s_mul_i32 s8, s15, 0x1080
	s_sub_u32 s8, s9, s8
	v_readfirstlane_b32 s16, v186
	s_subb_u32 s9, s14, 0
	s_ashr_i32 s18, s16, 6
	s_lshl_b32 s16, s18, 7
	s_ashr_i32 s17, s16, 31
	s_lshl_b64 s[16:17], s[16:17], 1
	s_lshl_b32 s14, s2, 3
	s_andn2_b32 s14, s14, 63
	s_lshl_b32 s100, s15, 12
	s_add_u32 s100, s100, s54
	s_addc_u32 s101, s55, 0
	s_add_u32 s100, s100, s16
	s_addc_u32 s101, s101, s17
	s_add_u32 s16, s16, s10
	s_addc_u32 s17, s17, s11
	s_lshl_b32 vcc_lo, s14, 11
	s_add_u32 s16, s16, vcc_lo
	s_addc_u32 s17, s17, 0
	s_lshl_b32 m0, s18, 14
	s_nop 0
	global_load_lds_dwordx4 v212, s[100:101]
	s_add_i32 m0, m0, 0x400
	s_nop 0
	global_load_lds_dwordx4 v213, s[100:101]
	s_add_i32 m0, m0, 0x400
	s_nop 0
	global_load_lds_dwordx4 v214, s[100:101]
	s_add_i32 m0, m0, 0x400
	s_nop 0
	global_load_lds_dwordx4 v215, s[100:101]
	s_add_i32 m0, m0, 0x400
	s_nop 0
	global_load_lds_dwordx4 v216, s[100:101]
	s_add_i32 m0, m0, 0x400
	s_nop 0
	global_load_lds_dwordx4 v217, s[100:101]
	s_add_i32 m0, m0, 0x400
	s_nop 0
	global_load_lds_dwordx4 v218, s[100:101]
	s_add_i32 m0, m0, 0x400
	s_nop 0
	global_load_lds_dwordx4 v219, s[100:101]
	s_add_i32 m0, m0, 0x400
	s_nop 0
	global_load_lds_dwordx4 v220, s[16:17]
	s_add_i32 m0, m0, 0x400
	s_nop 0
	global_load_lds_dwordx4 v221, s[16:17]
	s_add_i32 m0, m0, 0x400
	s_nop 0
	global_load_lds_dwordx4 v222, s[16:17]
	s_add_i32 m0, m0, 0x400
	s_nop 0
	global_load_lds_dwordx4 v223, s[16:17]
	s_add_i32 m0, m0, 0x400
	s_nop 0
	global_load_lds_dwordx4 v224, s[16:17]
	s_add_i32 m0, m0, 0x400
	s_nop 0
	global_load_lds_dwordx4 v225, s[16:17]
	s_add_i32 m0, m0, 0x400
	s_nop 0
	global_load_lds_dwordx4 v226, s[16:17]
	s_add_i32 m0, m0, 0x400
	s_nop 0
	global_load_lds_dwordx4 v227, s[16:17]
	global_load_dwordx4 v[80:83], v212, s[100:101] offset:128
	global_load_dwordx4 v[84:87], v213, s[100:101] offset:128
	global_load_dwordx4 v[88:91], v214, s[100:101] offset:128
	global_load_dwordx4 v[92:95], v215, s[100:101] offset:128
	global_load_dwordx4 v[96:99], v216, s[100:101] offset:128
	global_load_dwordx4 v[100:103], v217, s[100:101] offset:128
	global_load_dwordx4 v[104:107], v218, s[100:101] offset:128
	global_load_dwordx4 v[108:111], v219, s[100:101] offset:128
	global_load_dwordx4 v[112:115], v220, s[16:17] offset:128
	global_load_dwordx4 v[116:119], v221, s[16:17] offset:128
	global_load_dwordx4 v[120:123], v222, s[16:17] offset:128
	global_load_dwordx4 v[124:127], v223, s[16:17] offset:128
	global_load_dwordx4 v[136:139], v224, s[16:17] offset:128
	global_load_dwordx4 v[140:143], v225, s[16:17] offset:128
	global_load_dwordx4 v[144:147], v226, s[16:17] offset:128
	global_load_dwordx4 v[148:151], v227, s[16:17] offset:128
	s_waitcnt vmcnt(16)
; template <int NT, int ACT, int K>
; __device__ __forceinline__ void small_gemm_tile(LAS unsigned char* lds, const bf16* __restrict__ A, const bf16* __restrict__ Bt, bf16* __restrict__ O, int ldc, int lda, int ldb, const float* __restrict__ rs, int m0, int n0, int tid) {
;     ...
;     if constexpr (NCH == 1) {
;         bf16x8 fa[4][4], fb[4][NT];
; #pragma unroll
;         for (int s_ = 0; s_ < 4; ++s_) {
; #pragma unroll
;             for (int m = 0; m < 4; ++m) fa[s_][m] = *(const bf16x8*)(ap + (size_t)m * 16 * lda + s_ * 32);
; #pragma unroll
;             for (int n = 0; n < NT; ++n) fb[s_][n] = *(const bf16x8*)(bp + (size_t)n * 16 * ldb + s_ * 32); }
;         __builtin_amdgcn_sched_barrier(0);
; #pragma unroll
;         for (int s_ = 0; s_ < 4; ++s_)
; #pragma unroll
;             for (int m = 0; m < 4; ++m)
; #pragma unroll
;                 for (int n = 0; n < NT; ++n) acc[m][n] = __builtin_amdgcn_mfma_f32_16x16x32_bf16(fa[s_][m], fb[s_][n], acc[m][n], 0, 0, 0);
;         __builtin_amdgcn_sched_barrier(0);
	ds_read_b128 v[16:19], v228 offset:0
	ds_read_b128 v[20:23], v229 offset:0
	ds_read_b128 v[24:27], v228 offset:2048
	ds_read_b128 v[28:31], v229 offset:2048
	ds_read_b128 v[32:35], v228 offset:4096
	ds_read_b128 v[36:39], v229 offset:4096
	ds_read_b128 v[40:43], v228 offset:6144
	ds_read_b128 v[44:47], v229 offset:6144
	ds_read_b128 v[48:51], v228 offset:8192
	ds_read_b128 v[52:55], v229 offset:8192
	ds_read_b128 v[56:59], v228 offset:10240
	ds_read_b128 v[60:63], v229 offset:10240
	ds_read_b128 v[64:67], v228 offset:12288
	ds_read_b128 v[68:71], v229 offset:12288
	ds_read_b128 v[72:75], v228 offset:14336
	ds_read_b128 v[76:79], v229 offset:14336
	s_waitcnt lgkmcnt(0)
	s_waitcnt vmcnt(0)
	ds_write_b128 v234, v[80:83]
	ds_write_b128 v234, v[84:87] offset:1024
	ds_write_b128 v234, v[88:91] offset:2048
	ds_write_b128 v234, v[92:95] offset:3072
	ds_write_b128 v234, v[96:99] offset:4096
	ds_write_b128 v234, v[100:103] offset:5120
	ds_write_b128 v234, v[104:107] offset:6144
	ds_write_b128 v234, v[108:111] offset:7168
	ds_write_b128 v234, v[112:115] offset:8192
	ds_write_b128 v234, v[116:119] offset:9216
	ds_write_b128 v234, v[120:123] offset:10240
	ds_write_b128 v234, v[124:127] offset:11264
	ds_write_b128 v234, v[136:139] offset:12288
	ds_write_b128 v234, v[140:143] offset:13312
	ds_write_b128 v234, v[144:147] offset:14336
	ds_write_b128 v234, v[148:151] offset:15360
	v_mfma_f32_16x16x32_bf16 v[154:157], v[16:19], v[48:51], 0
	v_mfma_f32_16x16x32_bf16 v[158:161], v[16:19], v[56:59], 0
	v_mfma_f32_16x16x32_bf16 v[162:165], v[16:19], v[64:67], 0
	v_mfma_f32_16x16x32_bf16 v[16:19], v[16:19], v[72:75], 0
	v_mfma_f32_16x16x32_bf16 v[188:191], v[24:27], v[48:51], 0
	v_mfma_f32_16x16x32_bf16 v[192:195], v[24:27], v[56:59], 0
	v_mfma_f32_16x16x32_bf16 v[196:199], v[24:27], v[64:67], 0
	v_mfma_f32_16x16x32_bf16 v[24:27], v[24:27], v[72:75], 0
	v_mfma_f32_16x16x32_bf16 v[200:203], v[32:35], v[48:51], 0
	v_mfma_f32_16x16x32_bf16 v[204:207], v[32:35], v[56:59], 0
	v_mfma_f32_16x16x32_bf16 v[208:211], v[32:35], v[64:67], 0
	v_mfma_f32_16x16x32_bf16 v[32:35], v[32:35], v[72:75], 0
	v_mfma_f32_16x16x32_bf16 v[48:51], v[40:43], v[48:51], 0
	v_mfma_f32_16x16x32_bf16 v[56:59], v[40:43], v[56:59], 0
	v_mfma_f32_16x16x32_bf16 v[64:67], v[40:43], v[64:67], 0
	v_mfma_f32_16x16x32_bf16 v[40:43], v[40:43], v[72:75], 0
	v_mfma_f32_16x16x32_bf16 v[72:75], v[20:23], v[52:55], v[154:157]
	v_mfma_f32_16x16x32_bf16 v[154:157], v[20:23], v[60:63], v[158:161]
	v_mfma_f32_16x16x32_bf16 v[158:161], v[20:23], v[68:71], v[162:165]
	v_mfma_f32_16x16x32_bf16 v[16:19], v[20:23], v[76:79], v[16:19]
	v_mfma_f32_16x16x32_bf16 v[20:23], v[28:31], v[52:55], v[188:191]
	v_mfma_f32_16x16x32_bf16 v[162:165], v[28:31], v[60:63], v[192:195]
	v_mfma_f32_16x16x32_bf16 v[188:191], v[28:31], v[68:71], v[196:199]
	v_mfma_f32_16x16x32_bf16 v[24:27], v[28:31], v[76:79], v[24:27]
	v_mfma_f32_16x16x32_bf16 v[28:31], v[36:39], v[52:55], v[200:203]
	v_mfma_f32_16x16x32_bf16 v[192:195], v[36:39], v[60:63], v[204:207]
	v_mfma_f32_16x16x32_bf16 v[196:199], v[36:39], v[68:71], v[208:211]
	v_mfma_f32_16x16x32_bf16 v[32:35], v[36:39], v[76:79], v[32:35]
	v_mfma_f32_16x16x32_bf16 v[36:39], v[44:47], v[52:55], v[48:51]
	v_mfma_f32_16x16x32_bf16 v[48:51], v[44:47], v[60:63], v[56:59]
	v_mfma_f32_16x16x32_bf16 v[52:55], v[44:47], v[68:71], v[64:67]
	v_mfma_f32_16x16x32_bf16 v[40:43], v[44:47], v[76:79], v[40:43]
	s_waitcnt lgkmcnt(0)
	ds_read_b128 v[80:83], v228 offset:0
	ds_read_b128 v[84:87], v229 offset:0
	ds_read_b128 v[88:91], v228 offset:2048
	ds_read_b128 v[92:95], v229 offset:2048
	ds_read_b128 v[96:99], v228 offset:4096
	ds_read_b128 v[100:103], v229 offset:4096
	ds_read_b128 v[104:107], v228 offset:6144
	ds_read_b128 v[108:111], v229 offset:6144
	ds_read_b128 v[112:115], v228 offset:8192
	ds_read_b128 v[116:119], v229 offset:8192
	ds_read_b128 v[120:123], v228 offset:10240
	ds_read_b128 v[124:127], v229 offset:10240
	ds_read_b128 v[136:139], v228 offset:12288
	ds_read_b128 v[140:143], v229 offset:12288
	ds_read_b128 v[144:147], v228 offset:14336
	ds_read_b128 v[148:151], v229 offset:14336
	s_waitcnt lgkmcnt(0)
	v_mfma_f32_16x16x32_bf16 v[44:47], v[80:83], v[112:115], v[72:75]
	v_mfma_f32_16x16x32_bf16 v[56:59], v[80:83], v[120:123], v[154:157]
	v_mfma_f32_16x16x32_bf16 v[60:63], v[80:83], v[136:139], v[158:161]
	v_mfma_f32_16x16x32_bf16 v[16:19], v[80:83], v[144:147], v[16:19]
	v_mfma_f32_16x16x32_bf16 v[20:23], v[88:91], v[112:115], v[20:23]
	v_mfma_f32_16x16x32_bf16 v[64:67], v[88:91], v[120:123], v[162:165]
	v_mfma_f32_16x16x32_bf16 v[68:71], v[88:91], v[136:139], v[188:191]
	v_mfma_f32_16x16x32_bf16 v[24:27], v[88:91], v[144:147], v[24:27]
	v_mfma_f32_16x16x32_bf16 v[28:31], v[96:99], v[112:115], v[28:31]
	v_mfma_f32_16x16x32_bf16 v[72:75], v[96:99], v[120:123], v[192:195]
	v_mfma_f32_16x16x32_bf16 v[76:79], v[96:99], v[136:139], v[196:199]
	v_mfma_f32_16x16x32_bf16 v[32:35], v[96:99], v[144:147], v[32:35]
	v_mfma_f32_16x16x32_bf16 v[36:39], v[104:107], v[112:115], v[36:39]
	v_mfma_f32_16x16x32_bf16 v[48:51], v[104:107], v[120:123], v[48:51]
	v_mfma_f32_16x16x32_bf16 v[52:55], v[104:107], v[136:139], v[52:55]
	v_mfma_f32_16x16x32_bf16 v[40:43], v[104:107], v[144:147], v[40:43]
	v_mfma_f32_16x16x32_bf16 v[44:47], v[84:87], v[116:119], v[44:47]
	v_mfma_f32_16x16x32_bf16 v[56:59], v[84:87], v[124:127], v[56:59]
	v_mfma_f32_16x16x32_bf16 v[60:63], v[84:87], v[140:143], v[60:63]
	v_mfma_f32_16x16x32_bf16 v[16:19], v[84:87], v[148:151], v[16:19]
	v_mfma_f32_16x16x32_bf16 v[20:23], v[92:95], v[116:119], v[20:23]
	v_mfma_f32_16x16x32_bf16 v[64:67], v[92:95], v[124:127], v[64:67]
; #define LAS __attribute__((address_space(3)))
; #define SG_LD(buf, c) do { _Pragma("unroll") for (int s_ = 0; s_ < 2; ++s_) { \
;             _Pragma("unroll") for (int m = 0; m < 4; ++m) fa[buf][s_][m] = *(const bf16x8*)(ap + (size_t)m * 16 * lda + (c) * 64 + s_ * 32); \
;             _Pragma("unroll") for (int n = 0; n < NT; ++n) fb[buf][s_][n] = *(const bf16x8*)(bp + (size_t)n * 16 * ldb + (c) * 64 + s_ * 32); } } while (0)
; template <int NT, int ACT, int K>
; __device__ __forceinline__ void small_gemm_tile(LAS unsigned char* lds, const bf16* __restrict__ A, const bf16* __restrict__ Bt, bf16* __restrict__ O, int ldc, int lda, int ldb, const float* __restrict__ rs, int m0, int n0, int tid) {
;     ...
; #pragma unroll
;         for (int s_ = 0; s_ < 4; ++s_)
; #pragma unroll
;             for (int m = 0; m < 4; ++m)
; #pragma unroll
;                 for (int n = 0; n < NT; ++n) acc[m][n] = __builtin_amdgcn_mfma_f32_16x16x32_bf16(fa[s_][m], fb[s_][n], acc[m][n], 0, 0, 0);
;         __builtin_amdgcn_sched_barrier(0);
;     } else {
;         constexpr int NC2 = KW / 64;
;         bf16x8 fa[3][2][4], fb[3][2][NT];
;     ...
;         SG_LD(0, 0); SG_LD(1, 1);
;         __builtin_amdgcn_sched_barrier(0);
; #pragma unroll
;         for (int c = 0; c < NC2; ++c) {
;             if (c + 2 < NC2) SG_LD((c + 2) % 3, c + 2);
;             __builtin_amdgcn_sched_barrier(0);
; #pragma unroll
;             for (int s_ = 0; s_ < 2; ++s_)
; #pragma unroll
;                 for (int m = 0; m < 4; ++m)
; #pragma unroll
;                     for (int n = 0; n < NT; ++n) acc[m][n] = __builtin_amdgcn_mfma_f32_16x16x32_bf16(fa[c % 3][s_][m], fb[c % 3][s_][n], acc[m][n], 0, 0, 0);
;             __builtin_amdgcn_sched_barrier(0);
;         }
;     ...
;     }
;     LAS float* P = (LAS float*)lds + wave * (64 * NC);
; #pragma unroll
;     for (int m = 0; m < 4; ++m)
; #pragma unroll
;         for (int n = 0; n < NT; ++n)
; #pragma unroll
;             for (int i = 0; i < 4; ++i) P[(m * 16 + fq * 4 + i) * NC + n * 16 + fr] = acc[m][n][i];
;     __syncthreads();
	v_mfma_f32_16x16x32_bf16 v[68:71], v[92:95], v[140:143], v[68:71]
	v_mfma_f32_16x16x32_bf16 v[24:27], v[92:95], v[148:151], v[24:27]
	v_mfma_f32_16x16x32_bf16 v[28:31], v[100:103], v[116:119], v[28:31]
	v_mfma_f32_16x16x32_bf16 v[72:75], v[100:103], v[124:127], v[72:75]
	v_mfma_f32_16x16x32_bf16 v[76:79], v[100:103], v[140:143], v[76:79]
	v_mfma_f32_16x16x32_bf16 v[32:35], v[100:103], v[148:151], v[32:35]
	v_mfma_f32_16x16x32_bf16 v[36:39], v[108:111], v[116:119], v[36:39]
	v_mfma_f32_16x16x32_bf16 v[48:51], v[108:111], v[124:127], v[48:51]
	v_mfma_f32_16x16x32_bf16 v[52:55], v[108:111], v[140:143], v[52:55]
	v_mfma_f32_16x16x32_bf16 v[40:43], v[108:111], v[148:151], v[40:43]
	v_lshl_add_u32 v3, s18, 14, v15
	ds_write2_b32 v3, v44, v56 offset1:16
	ds_write2_b32 v3, v45, v57 offset0:64 offset1:80
	ds_write2_b32 v3, v46, v58 offset0:128 offset1:144
	ds_write2_b32 v3, v47, v59 offset0:192 offset1:208
	ds_write2_b32 v3, v60, v16 offset0:32 offset1:48
	ds_write2_b32 v3, v61, v17 offset0:96 offset1:112
	ds_write2_b32 v3, v62, v18 offset0:160 offset1:176
	ds_write2_b32 v3, v63, v19 offset0:224 offset1:240
	v_add_u32_e32 v16, 0x1000, v3
	v_add_u32_e32 v56, s15, v14
	ds_write2_b32 v16, v20, v64 offset1:16
	ds_write2_b32 v16, v21, v65 offset0:64 offset1:80
	ds_write2_b32 v16, v22, v66 offset0:128 offset1:144
	ds_write2_b32 v16, v23, v67 offset0:192 offset1:208
	ds_write2_b32 v16, v68, v24 offset0:32 offset1:48
	ds_write2_b32 v16, v69, v25 offset0:96 offset1:112
	ds_write2_b32 v16, v70, v26 offset0:160 offset1:176
	ds_write2_b32 v16, v71, v27 offset0:224 offset1:240
	v_add_u32_e32 v16, 0x2000, v3
	v_ashrrev_i32_e32 v57, 31, v56
	ds_write2_b32 v16, v28, v72 offset1:16
	ds_write2_b32 v16, v29, v73 offset0:64 offset1:80
	ds_write2_b32 v16, v30, v74 offset0:128 offset1:144
	ds_write2_b32 v16, v31, v75 offset0:192 offset1:208
	ds_write2_b32 v16, v76, v32 offset0:32 offset1:48
	ds_write2_b32 v16, v77, v33 offset0:96 offset1:112
	ds_write2_b32 v16, v78, v34 offset0:160 offset1:176
	ds_write2_b32 v16, v79, v35 offset0:224 offset1:240
	v_add_u32_e32 v3, 0x3000, v3
	v_lshl_add_u64 v[16:17], v[56:57], 2, s[82:83]
	ds_write2_b32 v3, v36, v48 offset1:16
	ds_write2_b32 v3, v37, v49 offset0:64 offset1:80
	ds_write2_b32 v3, v38, v50 offset0:128 offset1:144
	ds_write2_b32 v3, v39, v51 offset0:192 offset1:208
	ds_write2_b32 v3, v52, v40 offset0:32 offset1:48
	ds_write2_b32 v3, v53, v41 offset0:96 offset1:112
	ds_write2_b32 v3, v54, v42 offset0:160 offset1:176
	ds_write2_b32 v3, v55, v43 offset0:224 offset1:240
	s_waitcnt lgkmcnt(0)
	s_barrier
; #define LAS __attribute__((address_space(3)))
; __device__ __forceinline__ unsigned pk2(float lo, float hi) { return f2bf(lo) | (f2bf(hi) << 16); }
; template <int NT, int ACT, int K>
; __device__ __forceinline__ void small_gemm_tile(LAS unsigned char* lds, const bf16* __restrict__ A, const bf16* __restrict__ Bt, bf16* __restrict__ O, int ldc, int lda, int ldb, const float* __restrict__ rs, int m0, int n0, int tid) {
;     ...
;     __syncthreads();
;     constexpr int EPT = 64 * NC / 512;
;     const int e0 = tid * EPT, row = e0 / NC, col = e0 % NC;
;     float r[EPT];
; #pragma unroll
;     for (int j = 0; j < EPT; ++j) r[j] = 0.f;
; #pragma unroll
;     for (int w = 0; w < 8; ++w) { const LAS f32x4* q = (const LAS f32x4*)((LAS float*)lds + w * (64 * NC) + e0);
; #pragma unroll
;         for (int j = 0; j < EPT / 4; ++j) { const f32x4 v = q[j]; r[4 * j] += v[0]; r[4 * j + 1] += v[1]; r[4 * j + 2] += v[2]; r[4 * j + 3] += v[3]; } }
;     if (rs) { const float sc = rs[m0 + row];
; #pragma unroll
;         for (int j = 0; j < EPT; ++j) r[j] *= sc; }
;     if (ACT == 1) {
; #pragma unroll
;         for (int j = 0; j < EPT; ++j) { const float t = fmaxf(r[j], 0.f); r[j] = t * t; } }
;     bf16* op = O + (size_t)(m0 + row) * ldc + n0 + col;
;     if (EPT == 8) { v4u w; w.x = pk2(r[0], r[1]); w.y = pk2(r[2], r[3]); w.z = pk2(r[4 % EPT], r[5 % EPT]); w.w = pk2(r[6 % EPT], r[7 % EPT]); *(v4u*)op = w; }
;     else { v2u w; w.x = pk2(r[0], r[1]); w.y = pk2(r[2], r[3]); *(v2u*)op = w; }
;     __syncthreads();
	global_load_dword v58, v[16:17], off
	ds_read_b128 v[16:19], v5
	ds_read_b128 v[20:23], v5 offset:16
	ds_read_b128 v[24:27], v5 offset:16384
	ds_read_b128 v[28:31], v5 offset:16400
	ds_read_b128 v[32:35], v5 offset:32768
	s_waitcnt lgkmcnt(4)
	v_mov_b32_e32 v36, v16
	v_mov_b32_e32 v37, v18
	v_pk_add_f32 v[36:37], v[36:37], 0 op_sel_hi:[1,0]
	s_waitcnt lgkmcnt(2)
	v_mov_b32_e32 v38, v24
	v_mov_b32_e32 v39, v26
	v_pk_add_f32 v[40:41], v[36:37], v[38:39]
	ds_read_b128 v[36:39], v5 offset:32784
	v_mov_b32_e32 v18, v17
	v_pk_add_f32 v[16:17], v[18:19], 0 op_sel_hi:[1,0]
	v_mov_b32_e32 v26, v25
	s_waitcnt lgkmcnt(1)
	v_mov_b32_e32 v43, v34
	v_pk_add_f32 v[16:17], v[16:17], v[26:27]
	v_mov_b32_e32 v34, v33
	v_pk_add_f32 v[62:63], v[16:17], v[34:35]
	v_mov_b32_e32 v16, v20
	v_mov_b32_e32 v17, v22
	v_pk_add_f32 v[16:17], v[16:17], 0 op_sel_hi:[1,0]
	v_mov_b32_e32 v18, v28
	v_mov_b32_e32 v19, v30
	v_pk_add_f32 v[16:17], v[16:17], v[18:19]
	s_waitcnt lgkmcnt(0)
	v_mov_b32_e32 v18, v36
	v_mov_b32_e32 v19, v38
	v_mov_b32_e32 v22, v21
	v_pk_add_f32 v[64:65], v[16:17], v[18:19]
	v_pk_add_f32 v[16:17], v[22:23], 0 op_sel_hi:[1,0]
	v_mov_b32_e32 v30, v29
	v_mov_b32_e32 v42, v32
	v_pk_add_f32 v[16:17], v[16:17], v[30:31]
	v_mov_b32_e32 v38, v37
	v_pk_add_f32 v[60:61], v[40:41], v[42:43]
	v_pk_add_f32 v[66:67], v[16:17], v[38:39]
	ds_read_b128 v[16:19], v5 offset:49152
	ds_read_b128 v[20:23], v5 offset:49168
	ds_read_b128 v[24:27], v6
	ds_read_b128 v[28:31], v7
	ds_read_b128 v[32:35], v8
	ds_read_b128 v[36:39], v9
	ds_read_b128 v[40:43], v10
	ds_read_b128 v[44:47], v11
	ds_read_b128 v[48:51], v12
	ds_read_b128 v[52:55], v13
	v_mov_b64_e32 v[68:69], s[8:9]
	v_mad_i64_i32 v[56:57], s[8:9], v56, s78, v[68:69]
	s_waitcnt lgkmcnt(9)
	v_mov_b32_e32 v68, v16
	v_mov_b32_e32 v69, v18
	v_mov_b32_e32 v18, v17
	v_pk_add_f32 v[60:61], v[60:61], v[68:69]
	v_pk_add_f32 v[16:17], v[62:63], v[18:19]
	s_waitcnt lgkmcnt(7)
	v_mov_b32_e32 v18, v24
	v_mov_b32_e32 v19, v26
	v_pk_add_f32 v[18:19], v[60:61], v[18:19]
	v_mov_b32_e32 v26, v25
	s_waitcnt lgkmcnt(5)
	v_mov_b32_e32 v24, v32
	v_mov_b32_e32 v25, v34
	v_pk_add_f32 v[18:19], v[18:19], v[24:25]
	s_waitcnt lgkmcnt(3)
	v_mov_b32_e32 v24, v40
	v_mov_b32_e32 v25, v42
	v_pk_add_f32 v[18:19], v[18:19], v[24:25]
	s_waitcnt lgkmcnt(1)
	v_mov_b32_e32 v24, v48
	v_mov_b32_e32 v25, v50
	v_pk_add_f32 v[18:19], v[18:19], v[24:25]
	v_mov_b32_e32 v24, v20
	v_mov_b32_e32 v25, v22
	v_mov_b32_e32 v22, v21
	v_pk_add_f32 v[24:25], v[64:65], v[24:25]
	v_pk_add_f32 v[20:21], v[66:67], v[22:23]
	v_mov_b32_e32 v22, v28
	v_mov_b32_e32 v23, v30
	v_mov_b32_e32 v30, v29
	v_pk_add_f32 v[16:17], v[16:17], v[26:27]
	v_mov_b32_e32 v34, v33
	v_pk_add_f32 v[22:23], v[24:25], v[22:23]
	v_pk_add_f32 v[20:21], v[20:21], v[30:31]
	v_mov_b32_e32 v24, v36
	v_mov_b32_e32 v25, v38
	v_mov_b32_e32 v38, v37
	v_pk_add_f32 v[16:17], v[16:17], v[34:35]
	v_mov_b32_e32 v42, v41
	v_pk_add_f32 v[22:23], v[22:23], v[24:25]
	v_pk_add_f32 v[20:21], v[20:21], v[38:39]
	v_mov_b32_e32 v24, v44
	v_mov_b32_e32 v25, v46
	v_mov_b32_e32 v46, v45
	v_pk_add_f32 v[16:17], v[16:17], v[42:43]
	v_mov_b32_e32 v50, v49
	v_pk_add_f32 v[22:23], v[22:23], v[24:25]
	v_pk_add_f32 v[20:21], v[20:21], v[46:47]
	s_waitcnt lgkmcnt(0)
	v_mov_b32_e32 v25, v54
	v_mov_b32_e32 v54, v53
	v_pk_add_f32 v[16:17], v[16:17], v[50:51]
	v_mov_b32_e32 v24, v52
	v_pk_add_f32 v[20:21], v[20:21], v[54:55]
	s_waitcnt vmcnt(0)
	v_pk_mul_f32 v[16:17], v[58:59], v[16:17] op_sel_hi:[0,1]
	v_pk_add_f32 v[22:23], v[22:23], v[24:25]
	v_pk_mul_f32 v[20:21], v[58:59], v[20:21] op_sel_hi:[0,1]
	v_pk_mul_f32 v[18:19], v[58:59], v[18:19] op_sel_hi:[0,1]
	v_pk_mul_f32 v[22:23], v[58:59], v[22:23] op_sel_hi:[0,1]
	v_bfe_u32 v3, v21, 16, 1
	v_bfe_u32 v24, v20, 16, 1
	v_bfe_u32 v25, v17, 16, 1
	v_bfe_u32 v26, v16, 16, 1
	v_add3_u32 v16, v16, v26, s90
	v_add3_u32 v17, v17, v25, s90
	v_add3_u32 v20, v20, v24, s90
	v_add3_u32 v3, v21, v3, s90
	v_bfe_u32 v21, v18, 16, 1
	v_bfe_u32 v24, v19, 16, 1
	v_bfe_u32 v25, v22, 16, 1
	v_bfe_u32 v26, v23, 16, 1
	s_ashr_i32 s15, s14, 31
	v_add3_u32 v23, v23, v26, s90
	v_add3_u32 v22, v22, v25, s90
	v_add3_u32 v19, v19, v24, s90
	v_add3_u32 v18, v18, v21, s90
	v_lshl_add_u64 v[56:57], s[14:15], 1, v[56:57]
	v_lshrrev_b32_e32 v21, 16, v18
	v_lshrrev_b32_e32 v24, 16, v19
	v_lshrrev_b32_e32 v18, 16, v22
	v_lshrrev_b32_e32 v19, 16, v23
	s_add_i32 s2, s2, s3
	v_lshl_add_u64 v[56:57], v[0:1], 1, v[56:57]
	v_and_or_b32 v19, v3, s91, v19
	v_and_or_b32 v18, v20, s91, v18
	v_and_or_b32 v17, v17, s91, v24
	v_and_or_b32 v16, v16, s91, v21
	s_cmpk_gt_i32 s2, 0xff
	global_store_dwordx4 v[56:57], v[16:19], off
	s_barrier
	s_cbranch_scc0 .LBB0_496

; #define SG_LD(buf, c) do { _Pragma("unroll") for (int s_ = 0; s_ < 2; ++s_) { \
;             _Pragma("unroll") for (int m = 0; m < 4; ++m) fa[buf][s_][m] = *(const bf16x8*)(ap + (size_t)m * 16 * lda + (c) * 64 + s_ * 32); \
;             _Pragma("unroll") for (int n = 0; n < NT; ++n) fb[buf][s_][n] = *(const bf16x8*)(bp + (size_t)n * 16 * ldb + (c) * 64 + s_ * 32); } } while (0)
; template <int NT, int ACT, int K>
; __device__ __forceinline__ void small_gemm_tile(LAS unsigned char* lds, const bf16* __restrict__ A, const bf16* __restrict__ Bt, bf16* __restrict__ O, int ldc, int lda, int ldb, const float* __restrict__ rs, int m0, int n0, int tid) {
;     ...
;     const int wave = __builtin_amdgcn_readfirstlane(tid >> 6), lane = tid & 63, fr = lane & 15, fq = lane >> 4;
;     const bf16* ap = A + (size_t)(m0 + fr) * lda + wave * KW + fq * 8;
;     const bf16* bp = Bt + (size_t)(n0 + fr) * ldb + wave * KW + fq * 8;
;     f32x4 acc[4][NT];
; #pragma unroll
;     for (int m = 0; m < 4; ++m)
; #pragma unroll
;         for (int n = 0; n < NT; ++n) acc[m][n] = (f32x4){0.f, 0.f, 0.f, 0.f};
;     if constexpr (NCH == 1) {
;         bf16x8 fa[4][4], fb[4][NT];
; #pragma unroll
;         for (int s_ = 0; s_ < 4; ++s_) {
; #pragma unroll
;             for (int m = 0; m < 4; ++m) fa[s_][m] = *(const bf16x8*)(ap + (size_t)m * 16 * lda + s_ * 32);
; #pragma unroll
;             for (int n = 0; n < NT; ++n) fb[s_][n] = *(const bf16x8*)(bp + (size_t)n * 16 * ldb + s_ * 32); }
;         __builtin_amdgcn_sched_barrier(0);
; #pragma unroll
;         for (int s_ = 0; s_ < 4; ++s_)
; #pragma unroll
;             for (int m = 0; m < 4; ++m)
; #pragma unroll
;                 for (int n = 0; n < NT; ++n) acc[m][n] = __builtin_amdgcn_mfma_f32_16x16x32_bf16(fa[s_][m], fb[s_][n], acc[m][n], 0, 0, 0);
;         __builtin_amdgcn_sched_barrier(0);
;     } else {
;         constexpr int NC2 = KW / 64;
;         bf16x8 fa[3][2][4], fb[3][2][NT];
;     ...
;         SG_LD(0, 0); SG_LD(1, 1);
;         __builtin_amdgcn_sched_barrier(0);
; #pragma unroll
;         for (int c = 0; c < NC2; ++c) {
;             if (c + 2 < NC2) SG_LD((c + 2) % 3, c + 2);
;             __builtin_amdgcn_sched_barrier(0);
.LBB0_502:
	s_mov_b64 s[6:7], -1
	s_and_b64 vcc, exec, s[0:1]
	v_lshlrev_b32_e32 v4, 1, v0
	s_cbranch_vccz .LBB0_504
	s_and_b32 s7, s8, 0x1c0
	s_bitset1_b32 s7, 14
	v_readfirstlane_b32 s14, v186
	s_lshl_b32 s6, s9, 2
	s_andn2_b32 s6, s6, 31
	s_ashr_i32 s14, s14, 6
	s_lshl_b32 s16, s14, 10
	s_mov_b32 s17, 0
	s_mul_i32 s100, s7, 0x2080
	s_add_u32 s100, s100, s4
	s_addc_u32 s101, s5, 0
	s_add_u32 s100, s100, s16
	s_addc_u32 s101, s101, 0
	s_add_u32 s16, s16, s10
	s_addc_u32 s17, s17, s11
	s_lshl_b32 vcc_lo, s6, 13
	s_add_u32 s16, s16, vcc_lo
	s_addc_u32 s17, s17, 0
	v_and_b32_e32 v227, 63, v186
	v_lshrrev_b32_e32 v229, 3, v227
	v_and_b32_e32 v230, 7, v227
	v_lshrrev_b32_e32 v231, 1, v229
	v_xor_b32_e32 v230, v230, v231
	v_lshlrev_b32_e32 v230, 4, v230
	v_mul_u32_u24_e32 v231, 0x2080, v229
	v_or_b32_e32 v212, v231, v230
	v_mul_u32_u24_e32 v231, 0x2000, v229
	v_or_b32_e32 v220, v231, v230
	v_xor_b32_e32 v213, 64, v212
	v_add_u32_e32 v213, 0x10400, v213
	v_xor_b32_e32 v221, 64, v220
	v_add_u32_e32 v221, 0x10000, v221
	v_add_u32_e32 v214, 0x20800, v212
	v_add_u32_e32 v215, 0x20800, v213
	v_add_u32_e32 v216, 0x41000, v212
	v_add_u32_e32 v217, 0x41000, v213
	v_add_u32_e32 v218, 0x61800, v212
	v_add_u32_e32 v219, 0x61800, v213
	v_add_u32_e32 v222, 0x20000, v220
	v_add_u32_e32 v223, 0x20000, v221
	v_and_b32_e32 v229, 15, v227
	v_lshrrev_b32_e32 v230, 4, v227
	v_lshrrev_b32_e32 v231, 1, v229
	v_xor_b32_e32 v230, v230, v231
	v_lshlrev_b32_e32 v230, 4, v230
	v_lshl_or_b32 v224, v229, 7, v230
	v_lshrrev_b32_e32 v231, 6, v186
	v_lshl_add_u32 v224, v231, 14, v224
	v_xor_b32_e32 v225, 64, v224
	v_lshlrev_b32_e32 v226, 4, v227
	v_lshl_add_u32 v226, v231, 14, v226
	global_load_dwordx4 v[40:43], v212, s[100:101]
	global_load_dwordx4 v[44:47], v213, s[100:101]
	global_load_dwordx4 v[48:51], v214, s[100:101]
	global_load_dwordx4 v[52:55], v215, s[100:101]
	global_load_dwordx4 v[56:59], v216, s[100:101]
	global_load_dwordx4 v[60:63], v217, s[100:101]
	global_load_dwordx4 v[64:67], v218, s[100:101]
	global_load_dwordx4 v[68:71], v219, s[100:101]
	global_load_dwordx4 v[72:75], v220, s[16:17]
	global_load_dwordx4 v[76:79], v221, s[16:17]
	global_load_dwordx4 v[80:83], v222, s[16:17]
	global_load_dwordx4 v[84:87], v223, s[16:17]
	global_load_dwordx4 v[88:91], v212, s[100:101] offset:128
	global_load_dwordx4 v[92:95], v213, s[100:101] offset:128
	global_load_dwordx4 v[96:99], v214, s[100:101] offset:128
	global_load_dwordx4 v[100:103], v215, s[100:101] offset:128
	global_load_dwordx4 v[104:107], v216, s[100:101] offset:128
	global_load_dwordx4 v[108:111], v217, s[100:101] offset:128
	global_load_dwordx4 v[112:115], v218, s[100:101] offset:128
	global_load_dwordx4 v[116:119], v219, s[100:101] offset:128
	global_load_dwordx4 v[120:123], v220, s[16:17] offset:128
	global_load_dwordx4 v[124:127], v221, s[16:17] offset:128
	global_load_dwordx4 v[136:139], v222, s[16:17] offset:128
	global_load_dwordx4 v[140:143], v223, s[16:17] offset:128
	s_waitcnt vmcnt(12)
	ds_write_b128 v226, v[40:43]
	ds_write_b128 v226, v[44:47] offset:1024
	ds_write_b128 v226, v[48:51] offset:2048
	ds_write_b128 v226, v[52:55] offset:3072
	ds_write_b128 v226, v[56:59] offset:4096
	ds_write_b128 v226, v[60:63] offset:5120
	ds_write_b128 v226, v[64:67] offset:6144
	ds_write_b128 v226, v[68:71] offset:7168
	ds_write_b128 v226, v[72:75] offset:8192
	ds_write_b128 v226, v[76:79] offset:9216
	ds_write_b128 v226, v[80:83] offset:10240
	ds_write_b128 v226, v[84:87] offset:11264
	s_waitcnt lgkmcnt(0)
	global_load_dwordx4 v[40:43], v212, s[100:101] offset:256
	global_load_dwordx4 v[44:47], v213, s[100:101] offset:256
	global_load_dwordx4 v[48:51], v214, s[100:101] offset:256
	global_load_dwordx4 v[52:55], v215, s[100:101] offset:256
	global_load_dwordx4 v[56:59], v216, s[100:101] offset:256
	global_load_dwordx4 v[60:63], v217, s[100:101] offset:256
	global_load_dwordx4 v[64:67], v218, s[100:101] offset:256
	global_load_dwordx4 v[68:71], v219, s[100:101] offset:256
	global_load_dwordx4 v[72:75], v220, s[16:17] offset:256
	global_load_dwordx4 v[76:79], v221, s[16:17] offset:256
	global_load_dwordx4 v[80:83], v222, s[16:17] offset:256
	global_load_dwordx4 v[84:87], v223, s[16:17] offset:256
	ds_read_b128 v[144:147], v224 offset:0
	ds_read_b128 v[148:151], v225 offset:0
	ds_read_b128 v[154:157], v224 offset:2048
	ds_read_b128 v[158:161], v225 offset:2048
	ds_read_b128 v[162:165], v224 offset:4096
	ds_read_b128 v[188:191], v225 offset:4096
	ds_read_b128 v[192:195], v224 offset:6144
	ds_read_b128 v[196:199], v225 offset:6144
	ds_read_b128 v[200:203], v224 offset:8192
	ds_read_b128 v[204:207], v225 offset:8192
	ds_read_b128 v[208:211], v224 offset:10240
	ds_read_b128 v[232:235], v225 offset:10240
	s_waitcnt lgkmcnt(0)
	v_mfma_f32_16x16x32_bf16 v[36:39], v[144:147], v[200:203], 0
	v_mfma_f32_16x16x32_bf16 v[8:11], v[144:147], v[208:211], 0
	v_mfma_f32_16x16x32_bf16 v[12:15], v[154:157], v[200:203], 0
	v_mfma_f32_16x16x32_bf16 v[16:19], v[154:157], v[208:211], 0
	v_mfma_f32_16x16x32_bf16 v[20:23], v[162:165], v[200:203], 0
	v_mfma_f32_16x16x32_bf16 v[24:27], v[162:165], v[208:211], 0
	v_mfma_f32_16x16x32_bf16 v[28:31], v[192:195], v[200:203], 0
	v_mfma_f32_16x16x32_bf16 v[32:35], v[192:195], v[208:211], 0
	v_mfma_f32_16x16x32_bf16 v[36:39], v[148:151], v[204:207], v[36:39]
	v_mfma_f32_16x16x32_bf16 v[8:11], v[148:151], v[232:235], v[8:11]
	v_mfma_f32_16x16x32_bf16 v[12:15], v[158:161], v[204:207], v[12:15]
	v_mfma_f32_16x16x32_bf16 v[16:19], v[158:161], v[232:235], v[16:19]
	v_mfma_f32_16x16x32_bf16 v[20:23], v[188:191], v[204:207], v[20:23]
	v_mfma_f32_16x16x32_bf16 v[24:27], v[188:191], v[232:235], v[24:27]
	v_mfma_f32_16x16x32_bf16 v[28:31], v[196:199], v[204:207], v[28:31]
	v_mfma_f32_16x16x32_bf16 v[32:35], v[196:199], v[232:235], v[32:35]
	s_waitcnt vmcnt(12)
; #define SG_LD(buf, c) do { _Pragma("unroll") for (int s_ = 0; s_ < 2; ++s_) { \
;             _Pragma("unroll") for (int m = 0; m < 4; ++m) fa[buf][s_][m] = *(const bf16x8*)(ap + (size_t)m * 16 * lda + (c) * 64 + s_ * 32); \
;             _Pragma("unroll") for (int n = 0; n < NT; ++n) fb[buf][s_][n] = *(const bf16x8*)(bp + (size_t)n * 16 * ldb + (c) * 64 + s_ * 32); } } while (0)
; template <int NT, int ACT, int K>
; __device__ __forceinline__ void small_gemm_tile(LAS unsigned char* lds, const bf16* __restrict__ A, const bf16* __restrict__ Bt, bf16* __restrict__ O, int ldc, int lda, int ldb, const float* __restrict__ rs, int m0, int n0, int tid) {
;     ...
; #pragma unroll
;         for (int c = 0; c < NC2; ++c) {
;             if (c + 2 < NC2) SG_LD((c + 2) % 3, c + 2);
;             __builtin_amdgcn_sched_barrier(0);
; #pragma unroll
;             for (int s_ = 0; s_ < 2; ++s_)
; #pragma unroll
;                 for (int m = 0; m < 4; ++m)
; #pragma unroll
;                     for (int n = 0; n < NT; ++n) acc[m][n] = __builtin_amdgcn_mfma_f32_16x16x32_bf16(fa[c % 3][s_][m], fb[c % 3][s_][n], acc[m][n], 0, 0, 0);
;             __builtin_amdgcn_sched_barrier(0);
;         }
	ds_write_b128 v226, v[88:91]
	ds_write_b128 v226, v[92:95] offset:1024
	ds_write_b128 v226, v[96:99] offset:2048
	ds_write_b128 v226, v[100:103] offset:3072
	ds_write_b128 v226, v[104:107] offset:4096
	ds_write_b128 v226, v[108:111] offset:5120
	ds_write_b128 v226, v[112:115] offset:6144
	ds_write_b128 v226, v[116:119] offset:7168
	ds_write_b128 v226, v[120:123] offset:8192
	ds_write_b128 v226, v[124:127] offset:9216
	ds_write_b128 v226, v[136:139] offset:10240
	ds_write_b128 v226, v[140:143] offset:11264
	s_waitcnt lgkmcnt(0)
	global_load_dwordx4 v[88:91], v212, s[100:101] offset:384
	global_load_dwordx4 v[92:95], v213, s[100:101] offset:384
	global_load_dwordx4 v[96:99], v214, s[100:101] offset:384
	global_load_dwordx4 v[100:103], v215, s[100:101] offset:384
	global_load_dwordx4 v[104:107], v216, s[100:101] offset:384
	global_load_dwordx4 v[108:111], v217, s[100:101] offset:384
	global_load_dwordx4 v[112:115], v218, s[100:101] offset:384
	global_load_dwordx4 v[116:119], v219, s[100:101] offset:384
	global_load_dwordx4 v[120:123], v220, s[16:17] offset:384
	global_load_dwordx4 v[124:127], v221, s[16:17] offset:384
	global_load_dwordx4 v[136:139], v222, s[16:17] offset:384
	global_load_dwordx4 v[140:143], v223, s[16:17] offset:384
	ds_read_b128 v[144:147], v224 offset:0
	ds_read_b128 v[148:151], v225 offset:0
	ds_read_b128 v[154:157], v224 offset:2048
	ds_read_b128 v[158:161], v225 offset:2048
	ds_read_b128 v[162:165], v224 offset:4096
	ds_read_b128 v[188:191], v225 offset:4096
	ds_read_b128 v[192:195], v224 offset:6144
	ds_read_b128 v[196:199], v225 offset:6144
	ds_read_b128 v[200:203], v224 offset:8192
	ds_read_b128 v[204:207], v225 offset:8192
	ds_read_b128 v[208:211], v224 offset:10240
	ds_read_b128 v[232:235], v225 offset:10240
	s_waitcnt lgkmcnt(0)
	v_mfma_f32_16x16x32_bf16 v[36:39], v[144:147], v[200:203], v[36:39]
	v_mfma_f32_16x16x32_bf16 v[8:11], v[144:147], v[208:211], v[8:11]
	v_mfma_f32_16x16x32_bf16 v[12:15], v[154:157], v[200:203], v[12:15]
	v_mfma_f32_16x16x32_bf16 v[16:19], v[154:157], v[208:211], v[16:19]
	v_mfma_f32_16x16x32_bf16 v[20:23], v[162:165], v[200:203], v[20:23]
	v_mfma_f32_16x16x32_bf16 v[24:27], v[162:165], v[208:211], v[24:27]
	v_mfma_f32_16x16x32_bf16 v[28:31], v[192:195], v[200:203], v[28:31]
	v_mfma_f32_16x16x32_bf16 v[32:35], v[192:195], v[208:211], v[32:35]
	v_mfma_f32_16x16x32_bf16 v[36:39], v[148:151], v[204:207], v[36:39]
	v_mfma_f32_16x16x32_bf16 v[8:11], v[148:151], v[232:235], v[8:11]
	v_mfma_f32_16x16x32_bf16 v[12:15], v[158:161], v[204:207], v[12:15]
	v_mfma_f32_16x16x32_bf16 v[16:19], v[158:161], v[232:235], v[16:19]
	v_mfma_f32_16x16x32_bf16 v[20:23], v[188:191], v[204:207], v[20:23]
	v_mfma_f32_16x16x32_bf16 v[24:27], v[188:191], v[232:235], v[24:27]
	v_mfma_f32_16x16x32_bf16 v[28:31], v[196:199], v[204:207], v[28:31]
	v_mfma_f32_16x16x32_bf16 v[32:35], v[196:199], v[232:235], v[32:35]
	s_waitcnt vmcnt(12)
	ds_write_b128 v226, v[40:43]
	ds_write_b128 v226, v[44:47] offset:1024
	ds_write_b128 v226, v[48:51] offset:2048
	ds_write_b128 v226, v[52:55] offset:3072
	ds_write_b128 v226, v[56:59] offset:4096
	ds_write_b128 v226, v[60:63] offset:5120
	ds_write_b128 v226, v[64:67] offset:6144
	ds_write_b128 v226, v[68:71] offset:7168
	ds_write_b128 v226, v[72:75] offset:8192
	ds_write_b128 v226, v[76:79] offset:9216
	ds_write_b128 v226, v[80:83] offset:10240
	ds_write_b128 v226, v[84:87] offset:11264
	s_waitcnt lgkmcnt(0)
	global_load_dwordx4 v[40:43], v212, s[100:101] offset:512
	global_load_dwordx4 v[44:47], v213, s[100:101] offset:512
	global_load_dwordx4 v[48:51], v214, s[100:101] offset:512
	global_load_dwordx4 v[52:55], v215, s[100:101] offset:512
	global_load_dwordx4 v[56:59], v216, s[100:101] offset:512
	global_load_dwordx4 v[60:63], v217, s[100:101] offset:512
	global_load_dwordx4 v[64:67], v218, s[100:101] offset:512
	global_load_dwordx4 v[68:71], v219, s[100:101] offset:512
	global_load_dwordx4 v[72:75], v220, s[16:17] offset:512
	global_load_dwordx4 v[76:79], v221, s[16:17] offset:512
	global_load_dwordx4 v[80:83], v222, s[16:17] offset:512
	global_load_dwordx4 v[84:87], v223, s[16:17] offset:512
	ds_read_b128 v[144:147], v224 offset:0
	ds_read_b128 v[148:151], v225 offset:0
	ds_read_b128 v[154:157], v224 offset:2048
	ds_read_b128 v[158:161], v225 offset:2048
	ds_read_b128 v[162:165], v224 offset:4096
	ds_read_b128 v[188:191], v225 offset:4096
	ds_read_b128 v[192:195], v224 offset:6144
	ds_read_b128 v[196:199], v225 offset:6144
	ds_read_b128 v[200:203], v224 offset:8192
	ds_read_b128 v[204:207], v225 offset:8192
	ds_read_b128 v[208:211], v224 offset:10240
	ds_read_b128 v[232:235], v225 offset:10240
	s_waitcnt lgkmcnt(0)
	v_mfma_f32_16x16x32_bf16 v[36:39], v[144:147], v[200:203], v[36:39]
	v_mfma_f32_16x16x32_bf16 v[8:11], v[144:147], v[208:211], v[8:11]
	v_mfma_f32_16x16x32_bf16 v[12:15], v[154:157], v[200:203], v[12:15]
	v_mfma_f32_16x16x32_bf16 v[16:19], v[154:157], v[208:211], v[16:19]
	v_mfma_f32_16x16x32_bf16 v[20:23], v[162:165], v[200:203], v[20:23]
	v_mfma_f32_16x16x32_bf16 v[24:27], v[162:165], v[208:211], v[24:27]
	v_mfma_f32_16x16x32_bf16 v[28:31], v[192:195], v[200:203], v[28:31]
	v_mfma_f32_16x16x32_bf16 v[32:35], v[192:195], v[208:211], v[32:35]
	v_mfma_f32_16x16x32_bf16 v[36:39], v[148:151], v[204:207], v[36:39]
	v_mfma_f32_16x16x32_bf16 v[8:11], v[148:151], v[232:235], v[8:11]
	v_mfma_f32_16x16x32_bf16 v[12:15], v[158:161], v[204:207], v[12:15]
	v_mfma_f32_16x16x32_bf16 v[16:19], v[158:161], v[232:235], v[16:19]
	v_mfma_f32_16x16x32_bf16 v[20:23], v[188:191], v[204:207], v[20:23]
	v_mfma_f32_16x16x32_bf16 v[24:27], v[188:191], v[232:235], v[24:27]
	v_mfma_f32_16x16x32_bf16 v[28:31], v[196:199], v[204:207], v[28:31]
	v_mfma_f32_16x16x32_bf16 v[32:35], v[196:199], v[232:235], v[32:35]
	s_waitcnt vmcnt(12)
; #define SG_LD(buf, c) do { _Pragma("unroll") for (int s_ = 0; s_ < 2; ++s_) { \
;             _Pragma("unroll") for (int m = 0; m < 4; ++m) fa[buf][s_][m] = *(const bf16x8*)(ap + (size_t)m * 16 * lda + (c) * 64 + s_ * 32); \
;             _Pragma("unroll") for (int n = 0; n < NT; ++n) fb[buf][s_][n] = *(const bf16x8*)(bp + (size_t)n * 16 * ldb + (c) * 64 + s_ * 32); } } while (0)
; template <int NT, int ACT, int K>
; __device__ __forceinline__ void small_gemm_tile(LAS unsigned char* lds, const bf16* __restrict__ A, const bf16* __restrict__ Bt, bf16* __restrict__ O, int ldc, int lda, int ldb, const float* __restrict__ rs, int m0, int n0, int tid) {
;     ...
; #pragma unroll
;         for (int c = 0; c < NC2; ++c) {
;             if (c + 2 < NC2) SG_LD((c + 2) % 3, c + 2);
;             __builtin_amdgcn_sched_barrier(0);
; #pragma unroll
;             for (int s_ = 0; s_ < 2; ++s_)
; #pragma unroll
;                 for (int m = 0; m < 4; ++m)
; #pragma unroll
;                     for (int n = 0; n < NT; ++n) acc[m][n] = __builtin_amdgcn_mfma_f32_16x16x32_bf16(fa[c % 3][s_][m], fb[c % 3][s_][n], acc[m][n], 0, 0, 0);
;             __builtin_amdgcn_sched_barrier(0);
;         }
	ds_write_b128 v226, v[88:91]
	ds_write_b128 v226, v[92:95] offset:1024
	ds_write_b128 v226, v[96:99] offset:2048
	ds_write_b128 v226, v[100:103] offset:3072
	ds_write_b128 v226, v[104:107] offset:4096
	ds_write_b128 v226, v[108:111] offset:5120
	ds_write_b128 v226, v[112:115] offset:6144
	ds_write_b128 v226, v[116:119] offset:7168
	ds_write_b128 v226, v[120:123] offset:8192
	ds_write_b128 v226, v[124:127] offset:9216
	ds_write_b128 v226, v[136:139] offset:10240
	ds_write_b128 v226, v[140:143] offset:11264
	s_waitcnt lgkmcnt(0)
	global_load_dwordx4 v[88:91], v212, s[100:101] offset:640
	global_load_dwordx4 v[92:95], v213, s[100:101] offset:640
	global_load_dwordx4 v[96:99], v214, s[100:101] offset:640
	global_load_dwordx4 v[100:103], v215, s[100:101] offset:640
	global_load_dwordx4 v[104:107], v216, s[100:101] offset:640
	global_load_dwordx4 v[108:111], v217, s[100:101] offset:640
	global_load_dwordx4 v[112:115], v218, s[100:101] offset:640
	global_load_dwordx4 v[116:119], v219, s[100:101] offset:640
	global_load_dwordx4 v[120:123], v220, s[16:17] offset:640
	global_load_dwordx4 v[124:127], v221, s[16:17] offset:640
	global_load_dwordx4 v[136:139], v222, s[16:17] offset:640
	global_load_dwordx4 v[140:143], v223, s[16:17] offset:640
	ds_read_b128 v[144:147], v224 offset:0
	ds_read_b128 v[148:151], v225 offset:0
	ds_read_b128 v[154:157], v224 offset:2048
	ds_read_b128 v[158:161], v225 offset:2048
	ds_read_b128 v[162:165], v224 offset:4096
	ds_read_b128 v[188:191], v225 offset:4096
	ds_read_b128 v[192:195], v224 offset:6144
	ds_read_b128 v[196:199], v225 offset:6144
	ds_read_b128 v[200:203], v224 offset:8192
	ds_read_b128 v[204:207], v225 offset:8192
	ds_read_b128 v[208:211], v224 offset:10240
	ds_read_b128 v[232:235], v225 offset:10240
	s_waitcnt lgkmcnt(0)
	v_mfma_f32_16x16x32_bf16 v[36:39], v[144:147], v[200:203], v[36:39]
	v_mfma_f32_16x16x32_bf16 v[8:11], v[144:147], v[208:211], v[8:11]
	v_mfma_f32_16x16x32_bf16 v[12:15], v[154:157], v[200:203], v[12:15]
	v_mfma_f32_16x16x32_bf16 v[16:19], v[154:157], v[208:211], v[16:19]
	v_mfma_f32_16x16x32_bf16 v[20:23], v[162:165], v[200:203], v[20:23]
	v_mfma_f32_16x16x32_bf16 v[24:27], v[162:165], v[208:211], v[24:27]
	v_mfma_f32_16x16x32_bf16 v[28:31], v[192:195], v[200:203], v[28:31]
	v_mfma_f32_16x16x32_bf16 v[32:35], v[192:195], v[208:211], v[32:35]
	v_mfma_f32_16x16x32_bf16 v[36:39], v[148:151], v[204:207], v[36:39]
	v_mfma_f32_16x16x32_bf16 v[8:11], v[148:151], v[232:235], v[8:11]
	v_mfma_f32_16x16x32_bf16 v[12:15], v[158:161], v[204:207], v[12:15]
	v_mfma_f32_16x16x32_bf16 v[16:19], v[158:161], v[232:235], v[16:19]
	v_mfma_f32_16x16x32_bf16 v[20:23], v[188:191], v[204:207], v[20:23]
	v_mfma_f32_16x16x32_bf16 v[24:27], v[188:191], v[232:235], v[24:27]
	v_mfma_f32_16x16x32_bf16 v[28:31], v[196:199], v[204:207], v[28:31]
	v_mfma_f32_16x16x32_bf16 v[32:35], v[196:199], v[232:235], v[32:35]
	s_waitcnt vmcnt(12)
	ds_write_b128 v226, v[40:43]
	ds_write_b128 v226, v[44:47] offset:1024
	ds_write_b128 v226, v[48:51] offset:2048
	ds_write_b128 v226, v[52:55] offset:3072
	ds_write_b128 v226, v[56:59] offset:4096
	ds_write_b128 v226, v[60:63] offset:5120
	ds_write_b128 v226, v[64:67] offset:6144
	ds_write_b128 v226, v[68:71] offset:7168
	ds_write_b128 v226, v[72:75] offset:8192
	ds_write_b128 v226, v[76:79] offset:9216
	ds_write_b128 v226, v[80:83] offset:10240
	ds_write_b128 v226, v[84:87] offset:11264
	s_waitcnt lgkmcnt(0)
	global_load_dwordx4 v[40:43], v212, s[100:101] offset:768
	global_load_dwordx4 v[44:47], v213, s[100:101] offset:768
	global_load_dwordx4 v[48:51], v214, s[100:101] offset:768
	global_load_dwordx4 v[52:55], v215, s[100:101] offset:768
	global_load_dwordx4 v[56:59], v216, s[100:101] offset:768
	global_load_dwordx4 v[60:63], v217, s[100:101] offset:768
	global_load_dwordx4 v[64:67], v218, s[100:101] offset:768
	global_load_dwordx4 v[68:71], v219, s[100:101] offset:768
	global_load_dwordx4 v[72:75], v220, s[16:17] offset:768
	global_load_dwordx4 v[76:79], v221, s[16:17] offset:768
	global_load_dwordx4 v[80:83], v222, s[16:17] offset:768
	global_load_dwordx4 v[84:87], v223, s[16:17] offset:768
	ds_read_b128 v[144:147], v224 offset:0
	ds_read_b128 v[148:151], v225 offset:0
	ds_read_b128 v[154:157], v224 offset:2048
	ds_read_b128 v[158:161], v225 offset:2048
	ds_read_b128 v[162:165], v224 offset:4096
	ds_read_b128 v[188:191], v225 offset:4096
	ds_read_b128 v[192:195], v224 offset:6144
	ds_read_b128 v[196:199], v225 offset:6144
	ds_read_b128 v[200:203], v224 offset:8192
	ds_read_b128 v[204:207], v225 offset:8192
	ds_read_b128 v[208:211], v224 offset:10240
	ds_read_b128 v[232:235], v225 offset:10240
	s_waitcnt lgkmcnt(0)
	v_mfma_f32_16x16x32_bf16 v[36:39], v[144:147], v[200:203], v[36:39]
	v_mfma_f32_16x16x32_bf16 v[8:11], v[144:147], v[208:211], v[8:11]
	v_mfma_f32_16x16x32_bf16 v[12:15], v[154:157], v[200:203], v[12:15]
	v_mfma_f32_16x16x32_bf16 v[16:19], v[154:157], v[208:211], v[16:19]
	v_mfma_f32_16x16x32_bf16 v[20:23], v[162:165], v[200:203], v[20:23]
	v_mfma_f32_16x16x32_bf16 v[24:27], v[162:165], v[208:211], v[24:27]
	v_mfma_f32_16x16x32_bf16 v[28:31], v[192:195], v[200:203], v[28:31]
	v_mfma_f32_16x16x32_bf16 v[32:35], v[192:195], v[208:211], v[32:35]
	v_mfma_f32_16x16x32_bf16 v[36:39], v[148:151], v[204:207], v[36:39]
	v_mfma_f32_16x16x32_bf16 v[8:11], v[148:151], v[232:235], v[8:11]
	v_mfma_f32_16x16x32_bf16 v[12:15], v[158:161], v[204:207], v[12:15]
	v_mfma_f32_16x16x32_bf16 v[16:19], v[158:161], v[232:235], v[16:19]
	v_mfma_f32_16x16x32_bf16 v[20:23], v[188:191], v[204:207], v[20:23]
	v_mfma_f32_16x16x32_bf16 v[24:27], v[188:191], v[232:235], v[24:27]
	v_mfma_f32_16x16x32_bf16 v[28:31], v[196:199], v[204:207], v[28:31]
	v_mfma_f32_16x16x32_bf16 v[32:35], v[196:199], v[232:235], v[32:35]
	s_waitcnt vmcnt(12)
; #define SG_LD(buf, c) do { _Pragma("unroll") for (int s_ = 0; s_ < 2; ++s_) { \
;             _Pragma("unroll") for (int m = 0; m < 4; ++m) fa[buf][s_][m] = *(const bf16x8*)(ap + (size_t)m * 16 * lda + (c) * 64 + s_ * 32); \
;             _Pragma("unroll") for (int n = 0; n < NT; ++n) fb[buf][s_][n] = *(const bf16x8*)(bp + (size_t)n * 16 * ldb + (c) * 64 + s_ * 32); } } while (0)
; template <int NT, int ACT, int K>
; __device__ __forceinline__ void small_gemm_tile(LAS unsigned char* lds, const bf16* __restrict__ A, const bf16* __restrict__ Bt, bf16* __restrict__ O, int ldc, int lda, int ldb, const float* __restrict__ rs, int m0, int n0, int tid) {
;     ...
; #pragma unroll
;         for (int c = 0; c < NC2; ++c) {
;             if (c + 2 < NC2) SG_LD((c + 2) % 3, c + 2);
;             __builtin_amdgcn_sched_barrier(0);
; #pragma unroll
;             for (int s_ = 0; s_ < 2; ++s_)
; #pragma unroll
;                 for (int m = 0; m < 4; ++m)
; #pragma unroll
;                     for (int n = 0; n < NT; ++n) acc[m][n] = __builtin_amdgcn_mfma_f32_16x16x32_bf16(fa[c % 3][s_][m], fb[c % 3][s_][n], acc[m][n], 0, 0, 0);
;             __builtin_amdgcn_sched_barrier(0);
;         }
	ds_write_b128 v226, v[88:91]
	ds_write_b128 v226, v[92:95] offset:1024
	ds_write_b128 v226, v[96:99] offset:2048
	ds_write_b128 v226, v[100:103] offset:3072
	ds_write_b128 v226, v[104:107] offset:4096
	ds_write_b128 v226, v[108:111] offset:5120
	ds_write_b128 v226, v[112:115] offset:6144
	ds_write_b128 v226, v[116:119] offset:7168
	ds_write_b128 v226, v[120:123] offset:8192
	ds_write_b128 v226, v[124:127] offset:9216
	ds_write_b128 v226, v[136:139] offset:10240
	ds_write_b128 v226, v[140:143] offset:11264
	s_waitcnt lgkmcnt(0)
	global_load_dwordx4 v[88:91], v212, s[100:101] offset:896
	global_load_dwordx4 v[92:95], v213, s[100:101] offset:896
	global_load_dwordx4 v[96:99], v214, s[100:101] offset:896
	global_load_dwordx4 v[100:103], v215, s[100:101] offset:896
	global_load_dwordx4 v[104:107], v216, s[100:101] offset:896
	global_load_dwordx4 v[108:111], v217, s[100:101] offset:896
	global_load_dwordx4 v[112:115], v218, s[100:101] offset:896
	global_load_dwordx4 v[116:119], v219, s[100:101] offset:896
	global_load_dwordx4 v[120:123], v220, s[16:17] offset:896
	global_load_dwordx4 v[124:127], v221, s[16:17] offset:896
	global_load_dwordx4 v[136:139], v222, s[16:17] offset:896
	global_load_dwordx4 v[140:143], v223, s[16:17] offset:896
	ds_read_b128 v[144:147], v224 offset:0
	ds_read_b128 v[148:151], v225 offset:0
	ds_read_b128 v[154:157], v224 offset:2048
	ds_read_b128 v[158:161], v225 offset:2048
	ds_read_b128 v[162:165], v224 offset:4096
	ds_read_b128 v[188:191], v225 offset:4096
	ds_read_b128 v[192:195], v224 offset:6144
	ds_read_b128 v[196:199], v225 offset:6144
	ds_read_b128 v[200:203], v224 offset:8192
	ds_read_b128 v[204:207], v225 offset:8192
	ds_read_b128 v[208:211], v224 offset:10240
	ds_read_b128 v[232:235], v225 offset:10240
	s_waitcnt lgkmcnt(0)
	v_mfma_f32_16x16x32_bf16 v[36:39], v[144:147], v[200:203], v[36:39]
	v_mfma_f32_16x16x32_bf16 v[8:11], v[144:147], v[208:211], v[8:11]
	v_mfma_f32_16x16x32_bf16 v[12:15], v[154:157], v[200:203], v[12:15]
	v_mfma_f32_16x16x32_bf16 v[16:19], v[154:157], v[208:211], v[16:19]
	v_mfma_f32_16x16x32_bf16 v[20:23], v[162:165], v[200:203], v[20:23]
	v_mfma_f32_16x16x32_bf16 v[24:27], v[162:165], v[208:211], v[24:27]
	v_mfma_f32_16x16x32_bf16 v[28:31], v[192:195], v[200:203], v[28:31]
	v_mfma_f32_16x16x32_bf16 v[32:35], v[192:195], v[208:211], v[32:35]
	v_mfma_f32_16x16x32_bf16 v[36:39], v[148:151], v[204:207], v[36:39]
	v_mfma_f32_16x16x32_bf16 v[8:11], v[148:151], v[232:235], v[8:11]
	v_mfma_f32_16x16x32_bf16 v[12:15], v[158:161], v[204:207], v[12:15]
	v_mfma_f32_16x16x32_bf16 v[16:19], v[158:161], v[232:235], v[16:19]
	v_mfma_f32_16x16x32_bf16 v[20:23], v[188:191], v[204:207], v[20:23]
	v_mfma_f32_16x16x32_bf16 v[24:27], v[188:191], v[232:235], v[24:27]
	v_mfma_f32_16x16x32_bf16 v[28:31], v[196:199], v[204:207], v[28:31]
	v_mfma_f32_16x16x32_bf16 v[32:35], v[196:199], v[232:235], v[32:35]
	s_waitcnt vmcnt(12)
	ds_write_b128 v226, v[40:43]
	ds_write_b128 v226, v[44:47] offset:1024
	ds_write_b128 v226, v[48:51] offset:2048
	ds_write_b128 v226, v[52:55] offset:3072
	ds_write_b128 v226, v[56:59] offset:4096
	ds_write_b128 v226, v[60:63] offset:5120
	ds_write_b128 v226, v[64:67] offset:6144
	ds_write_b128 v226, v[68:71] offset:7168
	ds_write_b128 v226, v[72:75] offset:8192
	ds_write_b128 v226, v[76:79] offset:9216
	ds_write_b128 v226, v[80:83] offset:10240
	ds_write_b128 v226, v[84:87] offset:11264
	s_waitcnt lgkmcnt(0)
	ds_read_b128 v[144:147], v224 offset:0
	ds_read_b128 v[148:151], v225 offset:0
	ds_read_b128 v[154:157], v224 offset:2048
	ds_read_b128 v[158:161], v225 offset:2048
	ds_read_b128 v[162:165], v224 offset:4096
	ds_read_b128 v[188:191], v225 offset:4096
	ds_read_b128 v[192:195], v224 offset:6144
	ds_read_b128 v[196:199], v225 offset:6144
	ds_read_b128 v[200:203], v224 offset:8192
	ds_read_b128 v[204:207], v225 offset:8192
	ds_read_b128 v[208:211], v224 offset:10240
	ds_read_b128 v[232:235], v225 offset:10240
	s_waitcnt lgkmcnt(0)
	v_mfma_f32_16x16x32_bf16 v[36:39], v[144:147], v[200:203], v[36:39]
	v_mfma_f32_16x16x32_bf16 v[8:11], v[144:147], v[208:211], v[8:11]
	v_mfma_f32_16x16x32_bf16 v[12:15], v[154:157], v[200:203], v[12:15]
	v_mfma_f32_16x16x32_bf16 v[16:19], v[154:157], v[208:211], v[16:19]
	v_mfma_f32_16x16x32_bf16 v[20:23], v[162:165], v[200:203], v[20:23]
	v_mfma_f32_16x16x32_bf16 v[24:27], v[162:165], v[208:211], v[24:27]
	v_mfma_f32_16x16x32_bf16 v[28:31], v[192:195], v[200:203], v[28:31]
	v_mfma_f32_16x16x32_bf16 v[32:35], v[192:195], v[208:211], v[32:35]
	v_mfma_f32_16x16x32_bf16 v[36:39], v[148:151], v[204:207], v[36:39]
	v_mfma_f32_16x16x32_bf16 v[8:11], v[148:151], v[232:235], v[8:11]
	v_mfma_f32_16x16x32_bf16 v[12:15], v[158:161], v[204:207], v[12:15]
	v_mfma_f32_16x16x32_bf16 v[16:19], v[158:161], v[232:235], v[16:19]
	v_mfma_f32_16x16x32_bf16 v[20:23], v[188:191], v[204:207], v[20:23]
	v_mfma_f32_16x16x32_bf16 v[24:27], v[188:191], v[232:235], v[24:27]
	v_mfma_f32_16x16x32_bf16 v[28:31], v[196:199], v[204:207], v[28:31]
	v_mfma_f32_16x16x32_bf16 v[32:35], v[196:199], v[232:235], v[32:35]
	s_waitcnt vmcnt(0)
	ds_write_b128 v226, v[88:91]
	ds_write_b128 v226, v[92:95] offset:1024
	ds_write_b128 v226, v[96:99] offset:2048
	ds_write_b128 v226, v[100:103] offset:3072
	ds_write_b128 v226, v[104:107] offset:4096
	ds_write_b128 v226, v[108:111] offset:5120
	ds_write_b128 v226, v[112:115] offset:6144
	ds_write_b128 v226, v[116:119] offset:7168
	ds_write_b128 v226, v[120:123] offset:8192
	ds_write_b128 v226, v[124:127] offset:9216
	ds_write_b128 v226, v[136:139] offset:10240
	ds_write_b128 v226, v[140:143] offset:11264
	s_waitcnt lgkmcnt(0)
	ds_read_b128 v[144:147], v224 offset:0
	ds_read_b128 v[148:151], v225 offset:0
	ds_read_b128 v[154:157], v224 offset:2048
	ds_read_b128 v[158:161], v225 offset:2048
	ds_read_b128 v[162:165], v224 offset:4096
	ds_read_b128 v[188:191], v225 offset:4096
	ds_read_b128 v[192:195], v224 offset:6144
	ds_read_b128 v[196:199], v225 offset:6144
	ds_read_b128 v[200:203], v224 offset:8192
	ds_read_b128 v[204:207], v225 offset:8192
	ds_read_b128 v[208:211], v224 offset:10240
	ds_read_b128 v[232:235], v225 offset:10240
	s_waitcnt lgkmcnt(0)
	s_barrier
; #define LAS __attribute__((address_space(3)))
; __device__ __forceinline__ unsigned pk2(float lo, float hi) { return f2bf(lo) | (f2bf(hi) << 16); }
; template <int NT, int ACT, int K>
; __device__ __forceinline__ void small_gemm_tile(LAS unsigned char* lds, const bf16* __restrict__ A, const bf16* __restrict__ Bt, bf16* __restrict__ O, int ldc, int lda, int ldb, const float* __restrict__ rs, int m0, int n0, int tid) {
;     ...
;             for (int s_ = 0; s_ < 2; ++s_)
; #pragma unroll
;                 for (int m = 0; m < 4; ++m)
; #pragma unroll
;                     for (int n = 0; n < NT; ++n) acc[m][n] = __builtin_amdgcn_mfma_f32_16x16x32_bf16(fa[c % 3][s_][m], fb[c % 3][s_][n], acc[m][n], 0, 0, 0);
;             __builtin_amdgcn_sched_barrier(0);
;         }
;     ...
;     }
;     LAS float* P = (LAS float*)lds + wave * (64 * NC);
; #pragma unroll
;     for (int m = 0; m < 4; ++m)
; #pragma unroll
;         for (int n = 0; n < NT; ++n)
; #pragma unroll
;             for (int i = 0; i < 4; ++i) P[(m * 16 + fq * 4 + i) * NC + n * 16 + fr] = acc[m][n][i];
;     __syncthreads();
;     constexpr int EPT = 64 * NC / 512;
;     const int e0 = tid * EPT, row = e0 / NC, col = e0 % NC;
;     float r[EPT];
; #pragma unroll
;     for (int j = 0; j < EPT; ++j) r[j] = 0.f;
; #pragma unroll
;     for (int w = 0; w < 8; ++w) { const LAS f32x4* q = (const LAS f32x4*)((LAS float*)lds + w * (64 * NC) + e0);
; #pragma unroll
;         for (int j = 0; j < EPT / 4; ++j) { const f32x4 v = q[j]; r[4 * j] += v[0]; r[4 * j + 1] += v[1]; r[4 * j + 2] += v[2]; r[4 * j + 3] += v[3]; } }
;     if (rs) { const float sc = rs[m0 + row];
; #pragma unroll
;         for (int j = 0; j < EPT; ++j) r[j] *= sc; }
;     if (ACT == 1) {
; #pragma unroll
;         for (int j = 0; j < EPT; ++j) { const float t = fmaxf(r[j], 0.f); r[j] = t * t; } }
;     bf16* op = O + (size_t)(m0 + row) * ldc + n0 + col;
;     if (EPT == 8) { v4u w; w.x = pk2(r[0], r[1]); w.y = pk2(r[2], r[3]); w.z = pk2(r[4 % EPT], r[5 % EPT]); w.w = pk2(r[6 % EPT], r[7 % EPT]); *(v4u*)op = w; }
;     else { v2u w; w.x = pk2(r[0], r[1]); w.y = pk2(r[2], r[3]); *(v2u*)op = w; }
;     __syncthreads();
	v_mfma_f32_16x16x32_bf16 v[36:39], v[144:147], v[200:203], v[36:39]
	v_mfma_f32_16x16x32_bf16 v[8:11], v[144:147], v[208:211], v[8:11]
	v_mfma_f32_16x16x32_bf16 v[12:15], v[154:157], v[200:203], v[12:15]
	v_mfma_f32_16x16x32_bf16 v[16:19], v[154:157], v[208:211], v[16:19]
	v_mfma_f32_16x16x32_bf16 v[20:23], v[162:165], v[200:203], v[20:23]
	v_mfma_f32_16x16x32_bf16 v[24:27], v[162:165], v[208:211], v[24:27]
	v_mfma_f32_16x16x32_bf16 v[28:31], v[192:195], v[200:203], v[28:31]
	v_mfma_f32_16x16x32_bf16 v[32:35], v[192:195], v[208:211], v[32:35]
	v_mfma_f32_16x16x32_bf16 v[36:39], v[148:151], v[204:207], v[36:39]
	v_mfma_f32_16x16x32_bf16 v[8:11], v[148:151], v[232:235], v[8:11]
	v_mfma_f32_16x16x32_bf16 v[12:15], v[158:161], v[204:207], v[12:15]
	v_mfma_f32_16x16x32_bf16 v[16:19], v[158:161], v[232:235], v[16:19]
	v_mfma_f32_16x16x32_bf16 v[20:23], v[188:191], v[204:207], v[20:23]
	v_mfma_f32_16x16x32_bf16 v[24:27], v[188:191], v[232:235], v[24:27]
	v_mfma_f32_16x16x32_bf16 v[28:31], v[196:199], v[204:207], v[28:31]
	v_mfma_f32_16x16x32_bf16 v[32:35], v[196:199], v[232:235], v[32:35]
	v_lshl_add_u32 v5, s14, 13, v7
	s_nop 0
	ds_write2_b32 v5, v36, v8 offset1:16
	ds_write2_b32 v5, v37, v9 offset0:32 offset1:48
	ds_write2_b32 v5, v38, v10 offset0:64 offset1:80
	ds_write2_b32 v5, v39, v11 offset0:96 offset1:112
	v_add_u32_e32 v8, 0x800, v5
	ds_write2_b32 v8, v12, v16 offset1:16
	ds_write2_b32 v8, v13, v17 offset0:32 offset1:48
	ds_write2_b32 v8, v14, v18 offset0:64 offset1:80
	ds_write2_b32 v8, v15, v19 offset0:96 offset1:112
	v_add_u32_e32 v8, 0x1000, v5
	v_add_u32_e32 v5, 0x1800, v5
	ds_write2_b32 v8, v20, v24 offset1:16
	ds_write2_b32 v8, v21, v25 offset0:32 offset1:48
	ds_write2_b32 v8, v22, v26 offset0:64 offset1:80
	ds_write2_b32 v8, v23, v27 offset0:96 offset1:112
	ds_write2_b32 v5, v28, v32 offset1:16
	ds_write2_b32 v5, v29, v33 offset0:32 offset1:48
	ds_write2_b32 v5, v30, v34 offset0:64 offset1:80
	ds_write2_b32 v5, v31, v35 offset0:96 offset1:112
	s_waitcnt lgkmcnt(0)
	s_barrier
	ds_read_b128 v[8:11], v1
	ds_read_b128 v[12:15], v1 offset:8192
	v_add_u32_e32 v36, s7, v6
	v_ashrrev_i32_e32 v37, 31, v36
	v_lshlrev_b64 v[36:37], 11, v[36:37]
	s_waitcnt lgkmcnt(1)
	v_mov_b32_e32 v16, v8
	v_mov_b32_e32 v17, v10
	v_mov_b32_e32 v10, v9
	v_pk_add_f32 v[16:17], v[16:17], 0 op_sel_hi:[1,0]
	s_waitcnt lgkmcnt(0)
	v_mov_b32_e32 v18, v12
	v_mov_b32_e32 v19, v14
	v_pk_add_f32 v[8:9], v[10:11], 0 op_sel_hi:[1,0]
	v_mov_b32_e32 v14, v13
	v_pk_add_f32 v[32:33], v[16:17], v[18:19]
	v_pk_add_f32 v[34:35], v[8:9], v[14:15]
	ds_read_b128 v[8:11], v1 offset:16384
	ds_read_b128 v[12:15], v1 offset:24576
	ds_read_b128 v[16:19], v1 offset:32768
	ds_read_b128 v[20:23], v1 offset:40960
	ds_read_b128 v[24:27], v1 offset:49152
	ds_read_b128 v[28:31], v1 offset:57344
	s_waitcnt lgkmcnt(5)
	v_mov_b32_e32 v38, v8
	v_mov_b32_e32 v39, v10
	v_mov_b32_e32 v10, v9
	v_pk_add_f32 v[32:33], v[32:33], v[38:39]
	v_pk_add_f32 v[8:9], v[34:35], v[10:11]
	s_waitcnt lgkmcnt(4)
	v_mov_b32_e32 v10, v12
	v_mov_b32_e32 v11, v14
	v_pk_add_f32 v[10:11], v[32:33], v[10:11]
	v_mov_b32_e32 v14, v13
	s_waitcnt lgkmcnt(3)
	v_mov_b32_e32 v12, v16
	v_mov_b32_e32 v13, v18
	v_pk_add_f32 v[8:9], v[8:9], v[14:15]
	v_pk_add_f32 v[10:11], v[10:11], v[12:13]
	v_mov_b32_e32 v18, v17
	s_waitcnt lgkmcnt(2)
	v_mov_b32_e32 v12, v20
	v_mov_b32_e32 v13, v22
	v_pk_add_f32 v[8:9], v[8:9], v[18:19]
	v_pk_add_f32 v[10:11], v[10:11], v[12:13]
	v_mov_b32_e32 v22, v21
	s_waitcnt lgkmcnt(1)
	v_mov_b32_e32 v12, v24
	v_mov_b32_e32 v13, v26
	v_pk_add_f32 v[8:9], v[8:9], v[22:23]
	v_pk_add_f32 v[10:11], v[10:11], v[12:13]
	v_mov_b32_e32 v26, v25
	s_waitcnt lgkmcnt(0)
	v_mov_b32_e32 v12, v28
	v_mov_b32_e32 v13, v30
	v_pk_add_f32 v[8:9], v[8:9], v[26:27]
	v_pk_add_f32 v[10:11], v[10:11], v[12:13]
	v_mov_b32_e32 v30, v29
	v_pk_add_f32 v[8:9], v[8:9], v[30:31]
	v_and_b32_sdwa v5, v11, v171 dst_sel:DWORD dst_unused:UNUSED_PAD src0_sel:WORD_1 src1_sel:DWORD
	v_and_b32_sdwa v12, v10, v171 dst_sel:DWORD dst_unused:UNUSED_PAD src0_sel:WORD_1 src1_sel:DWORD
	v_add3_u32 v10, v10, v12, s90
	v_add3_u32 v5, v11, v5, s90
	v_and_b32_sdwa v11, v9, v171 dst_sel:DWORD dst_unused:UNUSED_PAD src0_sel:WORD_1 src1_sel:DWORD
	v_and_b32_sdwa v12, v8, v171 dst_sel:DWORD dst_unused:UNUSED_PAD src0_sel:WORD_1 src1_sel:DWORD
	v_lshl_add_u64 v[36:37], s[12:13], 0, v[36:37]
	s_ashr_i32 s7, s6, 31
	v_add3_u32 v9, v9, v11, s90
	v_add3_u32 v8, v8, v12, s90
	v_lshl_add_u64 v[36:37], s[6:7], 1, v[36:37]
	v_and_b32_e32 v9, 0xffff0000, v9
	v_and_b32_e32 v8, 0xffff0000, v8
	v_lshl_add_u64 v[36:37], v[2:3], 1, v[36:37]
	v_or_b32_sdwa v9, v9, v5 dst_sel:DWORD dst_unused:UNUSED_PAD src0_sel:DWORD src1_sel:WORD_1
	v_or_b32_sdwa v8, v8, v10 dst_sel:DWORD dst_unused:UNUSED_PAD src0_sel:DWORD src1_sel:WORD_1
	global_store_dwordx2 v[36:37], v[8:9], off
	s_barrier
	s_mov_b64 s[6:7], 0
; template <int NT, int ACT, int K>
; __device__ __forceinline__ void small_gemm_tile(LAS unsigned char* lds, const bf16* __restrict__ A, const bf16* __restrict__ Bt, bf16* __restrict__ O, int ldc, int lda, int ldb, const float* __restrict__ rs, int m0, int n0, int tid) {
;     ...
;     const int wave = __builtin_amdgcn_readfirstlane(tid >> 6), lane = tid & 63, fr = lane & 15, fq = lane >> 4;
;     const bf16* ap = A + (size_t)(m0 + fr) * lda + wave * KW + fq * 8;
;     const bf16* bp = Bt + (size_t)(n0 + fr) * ldb + wave * KW + fq * 8;
;     f32x4 acc[4][NT];
; #pragma unroll
;     for (int m = 0; m < 4; ++m)
; #pragma unroll
;         for (int n = 0; n < NT; ++n) acc[m][n] = (f32x4){0.f, 0.f, 0.f, 0.f};
;     if constexpr (NCH == 1) {
;         bf16x8 fa[4][4], fb[4][NT];
; #pragma unroll
;         for (int s_ = 0; s_ < 4; ++s_) {
; #pragma unroll
;             for (int m = 0; m < 4; ++m) fa[s_][m] = *(const bf16x8*)(ap + (size_t)m * 16 * lda + s_ * 32);
; #pragma unroll
;             for (int n = 0; n < NT; ++n) fb[s_][n] = *(const bf16x8*)(bp + (size_t)n * 16 * ldb + s_ * 32); }
;         __builtin_amdgcn_sched_barrier(0);
; #pragma unroll
;         for (int s_ = 0; s_ < 4; ++s_)
; #pragma unroll
;             for (int m = 0; m < 4; ++m)
; #pragma unroll
;                 for (int n = 0; n < NT; ++n) acc[m][n] = __builtin_amdgcn_mfma_f32_16x16x32_bf16(fa[s_][m], fb[s_][n], acc[m][n], 0, 0, 0);
;         __builtin_amdgcn_sched_barrier(0);
.LBB0_504:
	s_andn2_b64 vcc, exec, s[6:7]
	s_cbranch_vccnz .LBB0_501
	s_and_b32 s6, s9, 7
	s_mul_i32 s7, s6, 0x82000
	s_lshl_b32 s6, s6, 6
	s_or_b32 s18, s6, 0x4000
	s_add_u32 s100, s34, s7
	s_addc_u32 s101, s35, 0
	s_add_u32 s100, s100, 0xf748000
	s_addc_u32 s101, s101, 0
	v_readfirstlane_b32 s7, v186
	s_lshl_b32 s6, s9, 2
	s_andn2_b32 s6, s6, 31
	s_ashr_i32 s7, s7, 6
	s_lshl_b32 s16, s7, 8
	s_add_u32 s100, s100, s16
	s_addc_u32 s101, s101, 0
	s_add_u32 s16, s16, s10
	s_addc_u32 s17, s11, 0
	s_lshl_b32 vcc_lo, s6, 11
	s_add_u32 s16, s16, vcc_lo
	s_addc_u32 s17, s17, 0
	v_and_b32_e32 v227, 63, v186
	v_lshrrev_b32_e32 v229, 3, v227
	v_and_b32_e32 v230, 7, v227
	v_lshrrev_b32_e32 v231, 1, v229
	v_xor_b32_e32 v230, v230, v231
	v_lshlrev_b32_e32 v230, 4, v230
	v_mul_u32_u24_e32 v231, 0x800, v229
	v_or_b32_e32 v212, v231, v230
	v_mul_u32_u24_e32 v231, 0x800, v229
	v_or_b32_e32 v220, v231, v230
	v_xor_b32_e32 v213, 64, v212
	v_add_u32_e32 v213, 0x4000, v213
	v_xor_b32_e32 v221, 64, v220
	v_add_u32_e32 v221, 0x4000, v221
	v_add_u32_e32 v214, 0x8000, v212
	v_add_u32_e32 v215, 0x8000, v213
	v_add_u32_e32 v216, 0x10000, v212
	v_add_u32_e32 v217, 0x10000, v213
	v_add_u32_e32 v218, 0x18000, v212
	v_add_u32_e32 v219, 0x18000, v213
	v_add_u32_e32 v222, 0x8000, v220
	v_add_u32_e32 v223, 0x8000, v221
	v_and_b32_e32 v229, 15, v227
	v_lshrrev_b32_e32 v230, 4, v227
	v_lshrrev_b32_e32 v231, 1, v229
	v_xor_b32_e32 v230, v230, v231
	v_lshlrev_b32_e32 v230, 4, v230
	v_lshl_or_b32 v224, v229, 7, v230
	v_lshrrev_b32_e32 v231, 6, v186
	v_lshl_add_u32 v224, v231, 14, v224
	v_xor_b32_e32 v225, 64, v224
	v_lshlrev_b32_e32 v226, 4, v227
	v_lshl_add_u32 v226, v231, 14, v226
	global_load_dwordx4 v[40:43], v212, s[100:101]
	global_load_dwordx4 v[44:47], v213, s[100:101]
	global_load_dwordx4 v[48:51], v214, s[100:101]
	global_load_dwordx4 v[52:55], v215, s[100:101]
	global_load_dwordx4 v[56:59], v216, s[100:101]
	global_load_dwordx4 v[60:63], v217, s[100:101]
	global_load_dwordx4 v[64:67], v218, s[100:101]
	global_load_dwordx4 v[68:71], v219, s[100:101]
	global_load_dwordx4 v[72:75], v220, s[16:17]
	global_load_dwordx4 v[76:79], v221, s[16:17]
	global_load_dwordx4 v[80:83], v222, s[16:17]
	global_load_dwordx4 v[84:87], v223, s[16:17]
	global_load_dwordx4 v[88:91], v212, s[100:101] offset:128
	global_load_dwordx4 v[92:95], v213, s[100:101] offset:128
	global_load_dwordx4 v[96:99], v214, s[100:101] offset:128
	global_load_dwordx4 v[100:103], v215, s[100:101] offset:128
	global_load_dwordx4 v[104:107], v216, s[100:101] offset:128
	global_load_dwordx4 v[108:111], v217, s[100:101] offset:128
	global_load_dwordx4 v[112:115], v218, s[100:101] offset:128
	global_load_dwordx4 v[116:119], v219, s[100:101] offset:128
	global_load_dwordx4 v[120:123], v220, s[16:17] offset:128
	global_load_dwordx4 v[124:127], v221, s[16:17] offset:128
	global_load_dwordx4 v[136:139], v222, s[16:17] offset:128
	global_load_dwordx4 v[140:143], v223, s[16:17] offset:128
	s_waitcnt vmcnt(12)
	ds_write_b128 v226, v[40:43]
	ds_write_b128 v226, v[44:47] offset:1024
	ds_write_b128 v226, v[48:51] offset:2048
	ds_write_b128 v226, v[52:55] offset:3072
	ds_write_b128 v226, v[56:59] offset:4096
	ds_write_b128 v226, v[60:63] offset:5120
	ds_write_b128 v226, v[64:67] offset:6144
	ds_write_b128 v226, v[68:71] offset:7168
	ds_write_b128 v226, v[72:75] offset:8192
	ds_write_b128 v226, v[76:79] offset:9216
	ds_write_b128 v226, v[80:83] offset:10240
	ds_write_b128 v226, v[84:87] offset:11264
	s_waitcnt lgkmcnt(0)
	ds_read_b128 v[144:147], v224 offset:0
	ds_read_b128 v[148:151], v225 offset:0
	ds_read_b128 v[154:157], v224 offset:2048
	ds_read_b128 v[158:161], v225 offset:2048
	ds_read_b128 v[162:165], v224 offset:4096
	ds_read_b128 v[188:191], v225 offset:4096
	ds_read_b128 v[192:195], v224 offset:6144
	ds_read_b128 v[196:199], v225 offset:6144
	ds_read_b128 v[200:203], v224 offset:8192
	ds_read_b128 v[204:207], v225 offset:8192
	ds_read_b128 v[208:211], v224 offset:10240
	ds_read_b128 v[232:235], v225 offset:10240
	s_waitcnt lgkmcnt(0)
	v_mfma_f32_16x16x32_bf16 v[28:31], v[144:147], v[200:203], 0
	v_mfma_f32_16x16x32_bf16 v[32:35], v[144:147], v[208:211], 0
	v_mfma_f32_16x16x32_bf16 v[36:39], v[154:157], v[200:203], 0
	v_mfma_f32_16x16x32_bf16 v[8:11], v[154:157], v[208:211], 0
	v_mfma_f32_16x16x32_bf16 v[12:15], v[162:165], v[200:203], 0
	v_mfma_f32_16x16x32_bf16 v[16:19], v[162:165], v[208:211], 0
	v_mfma_f32_16x16x32_bf16 v[20:23], v[192:195], v[200:203], 0
	v_mfma_f32_16x16x32_bf16 v[24:27], v[192:195], v[208:211], 0
	v_mfma_f32_16x16x32_bf16 v[28:31], v[148:151], v[204:207], v[28:31]
	v_mfma_f32_16x16x32_bf16 v[32:35], v[148:151], v[232:235], v[32:35]
	v_mfma_f32_16x16x32_bf16 v[36:39], v[158:161], v[204:207], v[36:39]
	v_mfma_f32_16x16x32_bf16 v[8:11], v[158:161], v[232:235], v[8:11]
	v_mfma_f32_16x16x32_bf16 v[12:15], v[188:191], v[204:207], v[12:15]
	v_mfma_f32_16x16x32_bf16 v[16:19], v[188:191], v[232:235], v[16:19]
	v_mfma_f32_16x16x32_bf16 v[20:23], v[196:199], v[204:207], v[20:23]
	v_mfma_f32_16x16x32_bf16 v[24:27], v[196:199], v[232:235], v[24:27]
	s_waitcnt vmcnt(0)
	ds_write_b128 v226, v[88:91]
	ds_write_b128 v226, v[92:95] offset:1024
	ds_write_b128 v226, v[96:99] offset:2048
	ds_write_b128 v226, v[100:103] offset:3072
	ds_write_b128 v226, v[104:107] offset:4096
	ds_write_b128 v226, v[108:111] offset:5120
	ds_write_b128 v226, v[112:115] offset:6144
	ds_write_b128 v226, v[116:119] offset:7168
	ds_write_b128 v226, v[120:123] offset:8192
	ds_write_b128 v226, v[124:127] offset:9216
	ds_write_b128 v226, v[136:139] offset:10240
	ds_write_b128 v226, v[140:143] offset:11264
	s_waitcnt lgkmcnt(0)
	ds_read_b128 v[144:147], v224 offset:0
	ds_read_b128 v[148:151], v225 offset:0
	ds_read_b128 v[154:157], v224 offset:2048
	ds_read_b128 v[158:161], v225 offset:2048
	ds_read_b128 v[162:165], v224 offset:4096
	ds_read_b128 v[188:191], v225 offset:4096
	ds_read_b128 v[192:195], v224 offset:6144
	ds_read_b128 v[196:199], v225 offset:6144
	ds_read_b128 v[200:203], v224 offset:8192
	ds_read_b128 v[204:207], v225 offset:8192
	ds_read_b128 v[208:211], v224 offset:10240
	ds_read_b128 v[232:235], v225 offset:10240
	s_waitcnt lgkmcnt(0)
	s_barrier
; template <int NT, int ACT, int K>
; __device__ __forceinline__ void small_gemm_tile(LAS unsigned char* lds, const bf16* __restrict__ A, const bf16* __restrict__ Bt, bf16* __restrict__ O, int ldc, int lda, int ldb, const float* __restrict__ rs, int m0, int n0, int tid) {
;     ...
; #pragma unroll
;         for (int s_ = 0; s_ < 4; ++s_)
; #pragma unroll
;             for (int m = 0; m < 4; ++m)
; #pragma unroll
;                 for (int n = 0; n < NT; ++n) acc[m][n] = __builtin_amdgcn_mfma_f32_16x16x32_bf16(fa[s_][m], fb[s_][n], acc[m][n], 0, 0, 0);
;         __builtin_amdgcn_sched_barrier(0);
;     } else {
;         constexpr int NC2 = KW / 64;
;         bf16x8 fa[3][2][4], fb[3][2][NT];
;     ...
;         SG_LD(0, 0); SG_LD(1, 1);
;         __builtin_amdgcn_sched_barrier(0);
; #pragma unroll
;         for (int c = 0; c < NC2; ++c) {
;             if (c + 2 < NC2) SG_LD((c + 2) % 3, c + 2);
;             __builtin_amdgcn_sched_barrier(0);
; #pragma unroll
;             for (int s_ = 0; s_ < 2; ++s_)
; #pragma unroll
;                 for (int m = 0; m < 4; ++m)
; #pragma unroll
;                     for (int n = 0; n < NT; ++n) acc[m][n] = __builtin_amdgcn_mfma_f32_16x16x32_bf16(fa[c % 3][s_][m], fb[c % 3][s_][n], acc[m][n], 0, 0, 0);
;             __builtin_amdgcn_sched_barrier(0);
;         }
;     ...
;     }
;     LAS float* P = (LAS float*)lds + wave * (64 * NC);
; #pragma unroll
;     for (int m = 0; m < 4; ++m)
; #pragma unroll
;         for (int n = 0; n < NT; ++n)
; #pragma unroll
;             for (int i = 0; i < 4; ++i) P[(m * 16 + fq * 4 + i) * NC + n * 16 + fr] = acc[m][n][i];
;     __syncthreads();
;     constexpr int EPT = 64 * NC / 512;
;     const int e0 = tid * EPT, row = e0 / NC, col = e0 % NC;
;     float r[EPT];
; #pragma unroll
;     for (int j = 0; j < EPT; ++j) r[j] = 0.f;
; #pragma unroll
;     for (int w = 0; w < 8; ++w) { const LAS f32x4* q = (const LAS f32x4*)((LAS float*)lds + w * (64 * NC) + e0);
; #pragma unroll
;         for (int j = 0; j < EPT / 4; ++j) { const f32x4 v = q[j]; r[4 * j] += v[0]; r[4 * j + 1] += v[1]; r[4 * j + 2] += v[2]; r[4 * j + 3] += v[3]; } }
;     if (rs) { const float sc = rs[m0 + row];
; #pragma unroll
;         for (int j = 0; j < EPT; ++j) r[j] *= sc; }
;     if (ACT == 1) {
; #pragma unroll
;         for (int j = 0; j < EPT; ++j) { const float t = fmaxf(r[j], 0.f); r[j] = t * t; } }
	v_mfma_f32_16x16x32_bf16 v[28:31], v[144:147], v[200:203], v[28:31]
	v_mfma_f32_16x16x32_bf16 v[32:35], v[144:147], v[208:211], v[32:35]
	v_mfma_f32_16x16x32_bf16 v[36:39], v[154:157], v[200:203], v[36:39]
	v_mfma_f32_16x16x32_bf16 v[8:11], v[154:157], v[208:211], v[8:11]
	v_mfma_f32_16x16x32_bf16 v[12:15], v[162:165], v[200:203], v[12:15]
	v_mfma_f32_16x16x32_bf16 v[16:19], v[162:165], v[208:211], v[16:19]
	v_mfma_f32_16x16x32_bf16 v[20:23], v[192:195], v[200:203], v[20:23]
	v_mfma_f32_16x16x32_bf16 v[24:27], v[192:195], v[208:211], v[24:27]
	v_mfma_f32_16x16x32_bf16 v[28:31], v[148:151], v[204:207], v[28:31]
	v_mfma_f32_16x16x32_bf16 v[32:35], v[148:151], v[232:235], v[32:35]
	v_mfma_f32_16x16x32_bf16 v[36:39], v[158:161], v[204:207], v[36:39]
	v_mfma_f32_16x16x32_bf16 v[8:11], v[158:161], v[232:235], v[8:11]
	v_mfma_f32_16x16x32_bf16 v[12:15], v[188:191], v[204:207], v[12:15]
	v_mfma_f32_16x16x32_bf16 v[16:19], v[188:191], v[232:235], v[16:19]
	v_mfma_f32_16x16x32_bf16 v[20:23], v[196:199], v[204:207], v[20:23]
	v_mfma_f32_16x16x32_bf16 v[24:27], v[196:199], v[232:235], v[24:27]
	v_lshl_add_u32 v4, s7, 13, v7
	v_add_u32_e32 v5, 0x800, v4
	ds_write2_b32 v4, v28, v32 offset1:16
	ds_write2_b32 v4, v29, v33 offset0:32 offset1:48
	ds_write2_b32 v4, v30, v34 offset0:64 offset1:80
	ds_write2_b32 v4, v31, v35 offset0:96 offset1:112
	ds_write2_b32 v5, v36, v8 offset1:16
	ds_write2_b32 v5, v37, v9 offset0:32 offset1:48
	ds_write2_b32 v5, v38, v10 offset0:64 offset1:80
	ds_write2_b32 v5, v39, v11 offset0:96 offset1:112
	v_add_u32_e32 v5, 0x1000, v4
	v_add_u32_e32 v4, 0x1800, v4
	ds_write2_b32 v5, v12, v16 offset1:16
	ds_write2_b32 v5, v13, v17 offset0:32 offset1:48
	ds_write2_b32 v5, v14, v18 offset0:64 offset1:80
	ds_write2_b32 v5, v15, v19 offset0:96 offset1:112
	ds_write2_b32 v4, v20, v24 offset1:16
	ds_write2_b32 v4, v21, v25 offset0:32 offset1:48
	ds_write2_b32 v4, v22, v26 offset0:64 offset1:80
	ds_write2_b32 v4, v23, v27 offset0:96 offset1:112
	s_waitcnt lgkmcnt(0)
	s_barrier
	ds_read_b128 v[8:11], v1
	ds_read_b128 v[12:15], v1 offset:8192
	v_add_u32_e32 v34, s18, v6
	v_ashrrev_i32_e32 v35, 31, v34
	v_lshlrev_b64 v[34:35], 11, v[34:35]
	s_waitcnt lgkmcnt(1)
	v_mov_b32_e32 v4, v8
	v_mov_b32_e32 v5, v10
	v_mov_b32_e32 v10, v9
	v_pk_add_f32 v[4:5], v[4:5], 0 op_sel_hi:[1,0]
	s_waitcnt lgkmcnt(0)
	v_mov_b32_e32 v16, v12
	v_mov_b32_e32 v17, v14
	v_pk_add_f32 v[8:9], v[10:11], 0 op_sel_hi:[1,0]
	v_mov_b32_e32 v14, v13
	v_pk_add_f32 v[4:5], v[4:5], v[16:17]
	v_pk_add_f32 v[32:33], v[8:9], v[14:15]
	ds_read_b128 v[8:11], v1 offset:16384
	ds_read_b128 v[12:15], v1 offset:24576
	ds_read_b128 v[16:19], v1 offset:32768
	ds_read_b128 v[20:23], v1 offset:40960
	ds_read_b128 v[24:27], v1 offset:49152
	ds_read_b128 v[28:31], v1 offset:57344
	s_waitcnt lgkmcnt(5)
	v_mov_b32_e32 v36, v8
	v_mov_b32_e32 v37, v10
	v_mov_b32_e32 v10, v9
	v_pk_add_f32 v[4:5], v[4:5], v[36:37]
	v_pk_add_f32 v[8:9], v[32:33], v[10:11]
	s_waitcnt lgkmcnt(4)
	v_mov_b32_e32 v10, v12
	v_mov_b32_e32 v11, v14
	v_pk_add_f32 v[4:5], v[4:5], v[10:11]
	v_mov_b32_e32 v14, v13
	s_waitcnt lgkmcnt(3)
	v_mov_b32_e32 v10, v16
	v_mov_b32_e32 v11, v18
	v_pk_add_f32 v[8:9], v[8:9], v[14:15]
	v_pk_add_f32 v[4:5], v[4:5], v[10:11]
	v_mov_b32_e32 v18, v17
	s_waitcnt lgkmcnt(2)
	v_mov_b32_e32 v10, v20
	v_mov_b32_e32 v11, v22
	v_pk_add_f32 v[8:9], v[8:9], v[18:19]
	v_pk_add_f32 v[4:5], v[4:5], v[10:11]
	v_mov_b32_e32 v22, v21
	s_waitcnt lgkmcnt(1)
	v_mov_b32_e32 v10, v24
	v_mov_b32_e32 v11, v26
	v_pk_add_f32 v[8:9], v[8:9], v[22:23]
	v_pk_add_f32 v[4:5], v[4:5], v[10:11]
	v_mov_b32_e32 v26, v25
	s_waitcnt lgkmcnt(0)
	v_mov_b32_e32 v10, v28
	v_mov_b32_e32 v11, v30
	v_pk_add_f32 v[8:9], v[8:9], v[26:27]
	v_pk_add_f32 v[4:5], v[4:5], v[10:11]
	v_mov_b32_e32 v30, v29
	v_pk_add_f32 v[8:9], v[8:9], v[30:31]
	v_and_b32_sdwa v10, v5, v171 dst_sel:DWORD dst_unused:UNUSED_PAD src0_sel:WORD_1 src1_sel:DWORD
	v_and_b32_sdwa v11, v4, v171 dst_sel:DWORD dst_unused:UNUSED_PAD src0_sel:WORD_1 src1_sel:DWORD
	v_add3_u32 v4, v4, v11, s90
	v_add3_u32 v5, v5, v10, s90
	v_and_b32_sdwa v10, v9, v171 dst_sel:DWORD dst_unused:UNUSED_PAD src0_sel:WORD_1 src1_sel:DWORD
	v_and_b32_sdwa v11, v8, v171 dst_sel:DWORD dst_unused:UNUSED_PAD src0_sel:WORD_1 src1_sel:DWORD
	v_lshl_add_u64 v[34:35], s[12:13], 0, v[34:35]
	s_ashr_i32 s7, s6, 31
	v_add3_u32 v9, v9, v10, s90
	v_add3_u32 v8, v8, v11, s90
	v_lshl_add_u64 v[34:35], s[6:7], 1, v[34:35]
	v_and_b32_e32 v9, 0xffff0000, v9
	v_and_b32_e32 v8, 0xffff0000, v8
	v_lshl_add_u64 v[34:35], v[2:3], 1, v[34:35]
	v_or_b32_sdwa v5, v9, v5 dst_sel:DWORD dst_unused:UNUSED_PAD src0_sel:DWORD src1_sel:WORD_1
	v_or_b32_sdwa v4, v8, v4 dst_sel:DWORD dst_unused:UNUSED_PAD src0_sel:DWORD src1_sel:WORD_1
	global_store_dwordx2 v[34:35], v[4:5], off
	s_barrier
	s_branch .LBB0_501
